# P4: the once-read gate tiles (mid and final epilogue) are loaded with the streaming hint (nt)
# speedup vs baseline: 1.0030x; 1.0030x over previous
; #define G_HALF(pl, ql, ps, qs, kt_) { const int k4_ = min((kt_) + 4, nk - 1); \
;         SB G_LOAD(pl, ql, k4_) F_LOAD(fa1, fb1, cur, 1) SB G_MFMA(fa0, fb0) SB G_STORE(ps, qs, wr) F_LOAD(fa0, fb0, nxt, 0) SB G_MFMA(fa1, fb1) SB \
;         __syncthreads(); { const int t_ = cur; cur = nxt; nxt = wr; wr = t_; } }
; #define G_HALF(pl, ql, ps, qs, kt_) { const int k4_ = min((kt_) + 4, nk - 1); \
;         SB R_BURST1(fb0, fb1, cur, 1, pl, ql, k4_, ps, qs, wr) R_BURST2(fb1, fb0, nxt, 0, ps, qs, wr) \
;         __syncthreads(); { const int t_ = cur; cur = nxt; nxt = wr; wr = t_; } }
; #define G_HALF(pl, ql, ps, qs, kt_) { const int k4_ = min((kt_) + 4, nk - 1); \
;         SB R_BURST1(fb0, fb1, cur, 1, pl, ql, k4_, ps, qs, wr) R_BURST2(fb1, fb0, nxt, 0, ps, qs, wr) \
;         __syncthreads(); { const int t_ = cur; cur = nxt; nxt = wr; wr = t_; } }
;     ...
; #pragma unroll 1
;     for (; kt + 3 <= nk; kt += 3) {
;         G_HALF(p1, q1, p2, q2, kt)
;         G_HALF(p2, q2, p0, q0, kt + 1)
;         G_HALF(p0, q0, p1, q1, kt + 2)
;     }
.LBB0_993:
	s_nop 0
	s_waitcnt lgkmcnt(4)
	v_mfma_f32_32x32x16_bf16 v[112:127], v[180:183], v[160:163], v[112:127]
	ds_read_b128 v[216:219], v195 offset:22560
	s_waitcnt vmcnt(7)
	ds_write_b128 v200, v[156:159]
	s_waitcnt lgkmcnt(5)
	v_mfma_f32_32x32x16_bf16 v[0:15], v[180:183], v[164:167], v[0:15]
	global_load_dwordx4 v[180:183], v250, s[98:99] offset:256
	ds_read_b128 v[156:159], v193 offset:2080
	s_waitcnt lgkmcnt(5)
	v_mfma_f32_32x32x16_bf16 v[96:111], v[176:179], v[160:163], v[96:111]
	ds_read_b128 v[222:225], v195 offset:25120
	s_waitcnt vmcnt(6)
	ds_write_b128 v199, v[152:155]
	v_mfma_f32_32x32x16_bf16 v[32:47], v[176:179], v[164:167], v[32:47]
	global_load_dwordx4 v[176:179], v251, s[98:99] offset:256
	ds_read_b128 v[152:155], v193 offset:4640
	s_waitcnt lgkmcnt(7)
	v_mfma_f32_32x32x16_bf16 v[80:95], v[172:175], v[160:163], v[80:95]
	s_waitcnt vmcnt(5)
	ds_write_b128 v196, v[148:151]
	v_mfma_f32_32x32x16_bf16 v[48:63], v[172:175], v[164:167], v[48:63]
	global_load_dwordx4 v[172:175], v250, s[100:101] offset:256
	ds_read_b128 v[148:151], v193 offset:7200
	s_waitcnt lgkmcnt(8)
	v_mfma_f32_32x32x16_bf16 v[64:79], v[168:171], v[160:163], v[64:79]
	s_waitcnt vmcnt(4)
	ds_write_b128 v198, v[144:147]
	v_mfma_f32_32x32x16_bf16 v[16:31], v[168:171], v[164:167], v[16:31]
	global_load_dwordx4 v[160:163], v251, s[100:101] offset:256
	ds_read_b128 v[144:147], v193 offset:9760
	s_waitcnt lgkmcnt(7)
	v_mfma_f32_32x32x16_bf16 v[112:127], v[156:159], v[216:219], v[112:127]
	ds_read_b128 v[164:167], v195 offset:63488
	s_waitcnt lgkmcnt(7)
	v_mfma_f32_32x32x16_bf16 v[0:15], v[156:159], v[222:225], v[0:15]
	ds_read_b128 v[156:159], v193 offset:43008
	s_waitcnt lgkmcnt(6)
	v_mfma_f32_32x32x16_bf16 v[96:111], v[152:155], v[216:219], v[96:111]
	ds_read_b128 v[168:171], v194 offset:43520
	v_mfma_f32_32x32x16_bf16 v[32:47], v[152:155], v[222:225], v[32:47]
	ds_read_b128 v[152:155], v193 offset:45568
	s_waitcnt lgkmcnt(6)
	v_mfma_f32_32x32x16_bf16 v[80:95], v[148:151], v[216:219], v[80:95]
	v_mfma_f32_32x32x16_bf16 v[48:63], v[148:151], v[222:225], v[48:63]
	ds_read_b128 v[148:151], v193 offset:48128
	s_waitcnt lgkmcnt(5)
	v_mfma_f32_32x32x16_bf16 v[64:79], v[144:147], v[216:219], v[64:79]
	v_mfma_f32_32x32x16_bf16 v[16:31], v[144:147], v[222:225], v[16:31]
	ds_read_b128 v[144:147], v193 offset:50688
	s_barrier
	s_min_u32 s6, s11, 26
	s_waitcnt lgkmcnt(4)
	v_mfma_f32_32x32x16_bf16 v[112:127], v[156:159], v[164:167], v[112:127]
	ds_read_b128 v[216:219], v195 offset:63520
	ds_write_b128 v192, v[140:143] offset:2048
	s_waitcnt lgkmcnt(5)
	v_mfma_f32_32x32x16_bf16 v[0:15], v[156:159], v[168:171], v[0:15]
	global_load_dwordx4 v[156:159], v250, s[98:99] offset:320
	ds_read_b128 v[140:143], v193 offset:43040
	s_waitcnt lgkmcnt(5)
	v_mfma_f32_32x32x16_bf16 v[96:111], v[152:155], v[164:167], v[96:111]
	ds_read_b128 v[222:225], v194 offset:43552
	ds_write_b128 v192, v[136:139] offset:12288
	v_mfma_f32_32x32x16_bf16 v[32:47], v[152:155], v[168:171], v[32:47]
	global_load_dwordx4 v[152:155], v251, s[98:99] offset:320
	ds_read_b128 v[136:139], v193 offset:45600
	s_waitcnt lgkmcnt(7)
	v_mfma_f32_32x32x16_bf16 v[80:95], v[148:151], v[164:167], v[80:95]
	ds_write_b128 v192, v[132:135] offset:22528
	v_mfma_f32_32x32x16_bf16 v[48:63], v[148:151], v[168:171], v[48:63]
	global_load_dwordx4 v[148:151], v250, s[100:101] offset:320
	ds_read_b128 v[132:135], v193 offset:48160
	s_waitcnt lgkmcnt(8)
	v_mfma_f32_32x32x16_bf16 v[64:79], v[144:147], v[164:167], v[64:79]
	s_waitcnt vmcnt(7)
	ds_write_b128 v192, v[128:131] offset:32768
	v_mfma_f32_32x32x16_bf16 v[16:31], v[144:147], v[168:171], v[16:31]
	global_load_dwordx4 v[144:147], v251, s[100:101] offset:320
	ds_read_b128 v[128:131], v193 offset:50720
	s_waitcnt lgkmcnt(7)
	v_mfma_f32_32x32x16_bf16 v[112:127], v[140:143], v[216:219], v[112:127]
	ds_read_b128 v[164:167], v202
	s_waitcnt lgkmcnt(7)
	v_mfma_f32_32x32x16_bf16 v[0:15], v[140:143], v[222:225], v[0:15]
	ds_read_b128 v[140:143], v201
	s_waitcnt lgkmcnt(6)
	v_mfma_f32_32x32x16_bf16 v[96:111], v[136:139], v[216:219], v[96:111]
	ds_read_b128 v[168:171], v203
	v_mfma_f32_32x32x16_bf16 v[32:47], v[136:139], v[222:225], v[32:47]
	ds_read_b128 v[136:139], v204
	s_waitcnt lgkmcnt(6)
	v_mfma_f32_32x32x16_bf16 v[80:95], v[132:135], v[216:219], v[80:95]
	v_mfma_f32_32x32x16_bf16 v[48:63], v[132:135], v[222:225], v[48:63]
	ds_read_b128 v[132:135], v205
	s_waitcnt lgkmcnt(5)
	v_mfma_f32_32x32x16_bf16 v[64:79], v[128:131], v[216:219], v[64:79]
	v_mfma_f32_32x32x16_bf16 v[16:31], v[128:131], v[222:225], v[16:31]
	ds_read_b128 v[128:131], v206
	s_barrier
; #define G_HALF(pl, ql, ps, qs, kt_) { const int k4_ = min((kt_) + 4, nk - 1); \
;         SB G_LOAD(pl, ql, k4_) F_LOAD(fa1, fb1, cur, 1) SB G_MFMA(fa0, fb0) SB G_STORE(ps, qs, wr) F_LOAD(fa0, fb0, nxt, 0) SB G_MFMA(fa1, fb1) SB \
;         __syncthreads(); { const int t_ = cur; cur = nxt; nxt = wr; wr = t_; } }
; #define G_HALF(pl, ql, ps, qs, kt_) { const int k4_ = min((kt_) + 4, nk - 1); \
;         SB R_BURST1(fb0, fb1, cur, 1, pl, ql, k4_, ps, qs, wr) R_BURST2(fb1, fb0, nxt, 0, ps, qs, wr) \
;         __syncthreads(); { const int t_ = cur; cur = nxt; nxt = wr; wr = t_; } }
; #define G_HALF(pl, ql, ps, qs, kt_) { const int k4_ = min((kt_) + 4, nk - 1); \
;         SB R_BURST1(fb0, fb1, cur, 1, pl, ql, k4_, ps, qs, wr) R_BURST2(fb1, fb0, nxt, 0, ps, qs, wr) \
;         __syncthreads(); { const int t_ = cur; cur = nxt; nxt = wr; wr = t_; } }
;     ...
; #pragma unroll 1
;     for (; kt + 3 <= nk; kt += 3) {
;         G_HALF(p1, q1, p2, q2, kt)
;         G_HALF(p2, q2, p0, q0, kt + 1)
;         G_HALF(p0, q0, p1, q1, kt + 2)
;     }
;     if (kt < nk) G_HALF(p1, q1, p2, q2, kt)
;     if (kt + 1 < nk) G_HALF(p2, q2, p0, q0, kt + 1)
	s_min_u32 s6, s11, 25
	s_waitcnt lgkmcnt(4)
	v_mfma_f32_32x32x16_bf16 v[112:127], v[140:143], v[164:167], v[112:127]
	ds_read_b128 v[216:219], v207
	s_waitcnt vmcnt(7)
	ds_write_b128 v192, v[180:183] offset:43008
	s_waitcnt lgkmcnt(5)
	v_mfma_f32_32x32x16_bf16 v[0:15], v[140:143], v[168:171], v[0:15]
	global_load_dwordx4 v[140:143], v250, s[98:99] offset:384
	ds_read_b128 v[180:183], v208
	s_waitcnt lgkmcnt(5)
	v_mfma_f32_32x32x16_bf16 v[96:111], v[136:139], v[164:167], v[96:111]
	ds_read_b128 v[222:225], v209
	s_waitcnt vmcnt(7)
	ds_write_b128 v192, v[176:179] offset:53248
	v_mfma_f32_32x32x16_bf16 v[32:47], v[136:139], v[168:171], v[32:47]
	ds_read_b128 v[176:179], v210
	global_load_dwordx4 v[136:139], v251, s[98:99] offset:384
	s_waitcnt lgkmcnt(7)
	v_mfma_f32_32x32x16_bf16 v[80:95], v[132:135], v[164:167], v[80:95]
	s_waitcnt vmcnt(7)
	ds_write_b128 v192, v[172:175] offset:63488
	v_mfma_f32_32x32x16_bf16 v[48:63], v[132:135], v[168:171], v[48:63]
	global_load_dwordx4 v[132:135], v250, s[100:101] offset:384
	ds_read_b128 v[172:175], v211
	s_waitcnt lgkmcnt(8)
	v_mfma_f32_32x32x16_bf16 v[64:79], v[128:131], v[164:167], v[64:79]
	s_waitcnt vmcnt(7)
	ds_write_b128 v197, v[160:163]
	v_mfma_f32_32x32x16_bf16 v[16:31], v[128:131], v[168:171], v[16:31]
	ds_read_b128 v[168:171], v214
	global_load_dwordx4 v[128:131], v251, s[100:101] offset:384
	s_waitcnt lgkmcnt(7)
	v_mfma_f32_32x32x16_bf16 v[112:127], v[180:183], v[216:219], v[112:127]
	ds_read_b128 v[160:163], v195 offset:22528
	s_waitcnt lgkmcnt(7)
	v_mfma_f32_32x32x16_bf16 v[0:15], v[180:183], v[222:225], v[0:15]
	ds_read_b128 v[180:183], v193 offset:2048
	s_waitcnt lgkmcnt(6)
	v_mfma_f32_32x32x16_bf16 v[96:111], v[176:179], v[216:219], v[96:111]
	ds_read_b128 v[164:167], v195 offset:25088
	v_mfma_f32_32x32x16_bf16 v[32:47], v[176:179], v[222:225], v[32:47]
	ds_read_b128 v[176:179], v193 offset:4608
	s_waitcnt lgkmcnt(6)
	v_mfma_f32_32x32x16_bf16 v[80:95], v[172:175], v[216:219], v[80:95]
	v_mfma_f32_32x32x16_bf16 v[48:63], v[172:175], v[222:225], v[48:63]
	ds_read_b128 v[172:175], v193 offset:7168
	s_waitcnt lgkmcnt(5)
	v_mfma_f32_32x32x16_bf16 v[64:79], v[168:171], v[216:219], v[64:79]
	v_mfma_f32_32x32x16_bf16 v[16:31], v[168:171], v[222:225], v[16:31]
	ds_read_b128 v[168:171], v193 offset:9728
	s_add_i32 s11, s11, 3
	v_add_u32_e32 v250, 0xc0, v250
	s_cmp_lt_u32 s11, 30
	v_add_u32_e32 v251, 0xc0, v251
	s_barrier
	s_cbranch_scc1 .LBB0_993
	s_waitcnt lgkmcnt(0)
	v_mfma_f32_32x32x16_bf16 v[112:127], v[180:183], v[160:163], v[112:127]
	ds_read_b128 v[184:187], v195 offset:22560
	s_waitcnt vmcnt(7)
	ds_write_b128 v200, v[156:159]
	v_mfma_f32_32x32x16_bf16 v[0:15], v[180:183], v[164:167], v[0:15]
	ds_read_b128 v[156:159], v193 offset:2080
	v_mfma_f32_32x32x16_bf16 v[96:111], v[176:179], v[160:163], v[96:111]
	ds_read_b128 v[180:183], v195 offset:25120
	s_waitcnt vmcnt(6)
	ds_write_b128 v199, v[152:155]
	v_mfma_f32_32x32x16_bf16 v[32:47], v[176:179], v[164:167], v[32:47]
	ds_read_b128 v[152:155], v193 offset:4640
	v_mfma_f32_32x32x16_bf16 v[80:95], v[172:175], v[160:163], v[80:95]
	s_waitcnt vmcnt(5)
	ds_write_b128 v196, v[148:151]
	v_mfma_f32_32x32x16_bf16 v[48:63], v[172:175], v[164:167], v[48:63]
	ds_read_b128 v[148:151], v193 offset:7200
	v_mfma_f32_32x32x16_bf16 v[64:79], v[168:171], v[160:163], v[64:79]
	s_waitcnt vmcnt(4)
	ds_write_b128 v198, v[144:147]
	v_mfma_f32_32x32x16_bf16 v[16:31], v[168:171], v[164:167], v[16:31]
	ds_read_b128 v[144:147], v193 offset:9760
	s_waitcnt lgkmcnt(7)
	v_mfma_f32_32x32x16_bf16 v[112:127], v[156:159], v[184:187], v[112:127]
	ds_read_b128 v[160:163], v195 offset:63488
	s_waitcnt lgkmcnt(7)
	v_mfma_f32_32x32x16_bf16 v[0:15], v[156:159], v[180:183], v[0:15]
	ds_read_b128 v[156:159], v193 offset:43008
	s_waitcnt lgkmcnt(6)
	v_mfma_f32_32x32x16_bf16 v[96:111], v[152:155], v[184:187], v[96:111]
	ds_read_b128 v[164:167], v194 offset:43520
	v_mfma_f32_32x32x16_bf16 v[32:47], v[152:155], v[180:183], v[32:47]
	ds_read_b128 v[152:155], v193 offset:45568
	s_waitcnt lgkmcnt(6)
	v_mfma_f32_32x32x16_bf16 v[80:95], v[148:151], v[184:187], v[80:95]
	v_mfma_f32_32x32x16_bf16 v[48:63], v[148:151], v[180:183], v[48:63]
	ds_read_b128 v[148:151], v193 offset:48128
	s_waitcnt lgkmcnt(5)
	v_mfma_f32_32x32x16_bf16 v[64:79], v[144:147], v[184:187], v[64:79]
	v_mfma_f32_32x32x16_bf16 v[16:31], v[144:147], v[180:183], v[16:31]
	ds_read_b128 v[144:147], v193 offset:50688
	s_waitcnt lgkmcnt(0)
	s_barrier
	v_mfma_f32_32x32x16_bf16 v[112:127], v[156:159], v[160:163], v[112:127]
	ds_read_b128 v[168:171], v195 offset:63520
	s_waitcnt vmcnt(3)
	ds_write_b128 v192, v[140:143] offset:2048
	v_mfma_f32_32x32x16_bf16 v[0:15], v[156:159], v[164:167], v[0:15]
	ds_read_b128 v[140:143], v193 offset:43040
	v_mfma_f32_32x32x16_bf16 v[96:111], v[152:155], v[160:163], v[96:111]
	ds_read_b128 v[156:159], v194 offset:43552
	s_waitcnt vmcnt(2)
	ds_write_b128 v192, v[136:139] offset:12288
	v_mfma_f32_32x32x16_bf16 v[32:47], v[152:155], v[164:167], v[32:47]
	ds_read_b128 v[136:139], v193 offset:45600
	v_mfma_f32_32x32x16_bf16 v[80:95], v[148:151], v[160:163], v[80:95]
	s_waitcnt vmcnt(1)
	ds_write_b128 v192, v[132:135] offset:22528
	v_mfma_f32_32x32x16_bf16 v[48:63], v[148:151], v[164:167], v[48:63]
	ds_read_b128 v[132:135], v193 offset:48160
	v_mfma_f32_32x32x16_bf16 v[64:79], v[144:147], v[160:163], v[64:79]
	s_waitcnt vmcnt(0)
	ds_write_b128 v192, v[128:131] offset:32768
	v_mfma_f32_32x32x16_bf16 v[16:31], v[144:147], v[164:167], v[16:31]
	ds_read_b128 v[128:131], v193 offset:50720
	s_waitcnt lgkmcnt(7)
	v_mfma_f32_32x32x16_bf16 v[112:127], v[140:143], v[168:171], v[112:127]
	s_waitcnt lgkmcnt(6)
	v_mfma_f32_32x32x16_bf16 v[0:15], v[140:143], v[156:159], v[0:15]
	s_waitcnt lgkmcnt(4)
	v_mfma_f32_32x32x16_bf16 v[96:111], v[136:139], v[168:171], v[96:111]
	v_mfma_f32_32x32x16_bf16 v[32:47], v[136:139], v[156:159], v[32:47]
	s_waitcnt lgkmcnt(2)
	v_mfma_f32_32x32x16_bf16 v[80:95], v[132:135], v[168:171], v[80:95]
	v_mfma_f32_32x32x16_bf16 v[48:63], v[132:135], v[156:159], v[48:63]
	s_waitcnt lgkmcnt(0)
	v_mfma_f32_32x32x16_bf16 v[64:79], v[128:131], v[168:171], v[64:79]
	v_mfma_f32_32x32x16_bf16 v[16:31], v[128:131], v[156:159], v[16:31]
	s_lshl_b32 s6, s53, 6
	s_add_i32 s14, s6, s14
	v_mov_b32_e32 v130, v220
	s_ashr_i32 s15, s14, 31
	s_barrier
; DI float bf_lo(unsigned u) { return __uint_as_float(u << 16); }
; DI float bf_hi(unsigned u) { return __uint_as_float(u & 0xffff0000u); }
; DI void phase4(const Params& p, unsigned char* smem, int tid) {
;     ...
;         {
;             int te = tid; asm volatile("" : "+v"(te));
;             const unsigned char* ga = ws + OFF_G + ((size_t)(f * 64 + tt) * 8 + (te >> 6)) * 16384 + (te & 63) * 16;
;             const unsigned char* gb = ga + (size_t)4 * 64 * 8 * 16384;
; #pragma unroll
;             for (int it = 0; it < 4; ++it)
; #pragma unroll
;                 for (int jt = 0; jt < 2; ++jt)
; #pragma unroll
;                     for (int gp = 0; gp < 2; ++gp) {
;                         const u32x4 a4 = *(const u32x4*)(ga + ((it * 2 + jt) * 2 + gp) * 1024), b4 = *(const u32x4*)(gb + ((it * 2 + jt) * 2 + gp) * 1024);
; #pragma unroll
;                         for (int e = 0; e < 4; ++e) {
;                             acc[it][jt][8 * gp + 2 * e] *= bf_lo(a4[e]) * __builtin_amdgcn_rcpf(fmaxf(bf_lo(b4[e]), 8.6736174e-19f));
;                             acc[it][jt][8 * gp + 2 * e + 1] *= bf_hi(a4[e]) * __builtin_amdgcn_rcpf(fmaxf(bf_hi(b4[e]), 8.6736174e-19f));
;                         }
;                     }
;         }
	s_lshl_b64 s[58:59], s[14:15], 17
	v_ashrrev_i32_e32 v128, 6, v130
	v_ashrrev_i32_e32 v129, 31, v128
	s_add_u32 s58, s24, s58
	v_lshlrev_b64 v[128:129], 14, v[128:129]
	s_addc_u32 s59, s25, s59
	v_lshlrev_b32_e32 v130, 4, v130
	v_lshl_add_u64 v[128:129], s[58:59], 0, v[128:129]
	v_and_b32_e32 v212, 0x3f0, v130
	v_lshl_add_u64 v[152:153], v[128:129], 0, v[212:213]
	v_add_co_u32_e32 v154, vcc, s41, v152
	global_load_dwordx4 v[132:135], v[152:153], off nt
	global_load_dwordx4 v[128:131], v[152:153], off offset:1024 nt
	v_addc_co_u32_e32 v155, vcc, 0, v153, vcc
	global_load_dwordx4 v[144:147], v[154:155], off offset:-4096 nt
	global_load_dwordx4 v[140:143], v[152:153], off offset:2048 nt
	v_add_co_u32_e32 v156, vcc, s39, v152
	v_mov_b32_e32 v210, v220
	s_nop 0
	v_addc_co_u32_e32 v157, vcc, 0, v153, vcc
	global_load_dwordx4 v[136:139], v[156:157], off offset:1024 nt
	v_add_co_u32_e32 v158, vcc, s44, v152
	s_add_u32 s58, s26, s55
	s_nop 0
	v_addc_co_u32_e32 v159, vcc, 0, v153, vcc
	global_load_dwordx4 v[148:151], v[156:157], off offset:2048 nt
	global_load_dwordx4 v[178:181], v[158:159], off offset:3072 nt
	s_addc_u32 s59, s27, 0
	s_add_u32 s18, s28, s18
	s_addc_u32 s19, s29, s19
	s_mov_b32 s11, 0
	s_waitcnt vmcnt(6)
	v_lshlrev_b32_e32 v160, 16, v132
	s_waitcnt vmcnt(5)
	v_lshlrev_b32_e32 v164, 16, v128
	v_and_b32_e32 v165, 0xffff0000, v128
	v_and_b32_e32 v161, 0xffff0000, v132
	s_waitcnt vmcnt(4)
	v_lshlrev_b32_e32 v166, 16, v145
	v_and_b32_e32 v145, 0xffff0000, v145
	v_lshlrev_b32_e32 v167, 16, v146
	v_and_b32_e32 v146, 0xffff0000, v146
	v_lshlrev_b32_e32 v168, 16, v147
	v_and_b32_e32 v147, 0xffff0000, v147
	v_max_f32_e32 v166, v166, v166
	v_max_f32_e32 v145, v145, v145
	v_max_f32_e32 v146, v146, v146
	v_max_f32_e32 v147, v147, v147
	v_max_f32_e32 v166, 0x21800000, v166
	v_max_f32_e32 v171, 0x21800000, v145
	v_lshlrev_b32_e32 v128, 16, v144
	v_max_f32_e32 v173, 0x21800000, v146
	v_max_f32_e32 v174, 0x21800000, v147
	v_rcp_f32_e32 v146, v166
	v_rcp_f32_e32 v147, v171
	v_and_b32_e32 v144, 0xffff0000, v144
	v_max_f32_e32 v128, v128, v128
	s_waitcnt vmcnt(2)
	v_lshlrev_b32_e32 v172, 16, v137
	v_max_f32_e32 v144, v144, v144
	v_max_f32_e32 v128, 0x21800000, v128
	v_lshlrev_b32_e32 v132, 16, v133
	v_and_b32_e32 v133, 0xffff0000, v133
	v_max_f32_e32 v170, 0x21800000, v144
	v_rcp_f32_e32 v144, v128
	v_max_f32_e32 v128, v172, v172
	v_pk_mul_f32 v[132:133], v[146:147], v[132:133]
	v_max_f32_e32 v128, 0x21800000, v128
	v_pk_mul_f32 v[114:115], v[114:115], v[132:133]
	v_rcp_f32_e32 v132, v128
	v_and_b32_e32 v128, 0xffff0000, v137
	v_max_f32_e32 v128, v128, v128
	v_max_f32_e32 v128, 0x21800000, v128
	v_lshlrev_b32_e32 v169, 16, v136
	v_max_f32_e32 v168, v168, v168
	v_rcp_f32_e32 v133, v128
	v_max_f32_e32 v169, v169, v169
	v_max_f32_e32 v168, 0x21800000, v168
	v_max_f32_e32 v175, 0x21800000, v169
	v_rcp_f32_e32 v168, v168
	v_rcp_f32_e32 v169, v174
	v_lshlrev_b32_e32 v128, 16, v129
	v_and_b32_e32 v129, 0xffff0000, v129
	v_and_b32_e32 v136, 0xffff0000, v136
	v_pk_mul_f32 v[128:129], v[132:133], v[128:129]
	v_lshlrev_b32_e32 v132, 16, v138
	v_lshlrev_b32_e32 v162, 16, v134
	v_and_b32_e32 v163, 0xffff0000, v134
	v_lshlrev_b32_e32 v134, 16, v135
	v_and_b32_e32 v135, 0xffff0000, v135
	v_max_f32_e32 v136, v136, v136
	v_max_f32_e32 v132, v132, v132
	v_max_f32_e32 v167, v167, v167
	v_max_f32_e32 v136, 0x21800000, v136
	v_pk_mul_f32 v[134:135], v[168:169], v[134:135]
	v_max_f32_e32 v132, 0x21800000, v132
	v_max_f32_e32 v167, 0x21800000, v167
	v_rcp_f32_e32 v171, v136
	v_pk_mul_f32 v[118:119], v[118:119], v[134:135]
	v_rcp_f32_e32 v136, v132
	global_load_dwordx4 v[132:135], v[156:157], off offset:3072 nt
	v_rcp_f32_e32 v145, v170
	v_rcp_f32_e32 v166, v167
	v_rcp_f32_e32 v167, v173
	v_and_b32_e32 v137, 0xffff0000, v138
	v_pk_mul_f32 v[144:145], v[144:145], v[160:161]
	v_max_f32_e32 v137, v137, v137
	v_pk_mul_f32 v[146:147], v[166:167], v[162:163]
	v_pk_mul_f32 v[112:113], v[112:113], v[144:145]
	v_pk_mul_f32 v[116:117], v[116:117], v[146:147]
	global_load_dwordx4 v[144:147], v[152:153], off offset:3072 nt
	v_max_f32_e32 v137, 0x21800000, v137
	v_rcp_f32_e32 v137, v137
	v_pk_mul_f32 v[122:123], v[122:123], v[128:129]
	v_lshlrev_b32_e32 v128, 16, v130
	v_and_b32_e32 v129, 0xffff0000, v130
	v_lshlrev_b32_e32 v130, 16, v139
	v_max_f32_e32 v130, v130, v130
	v_max_f32_e32 v130, 0x21800000, v130
	v_pk_mul_f32 v[128:129], v[136:137], v[128:129]
	v_rcp_f32_e32 v136, v130
	v_and_b32_e32 v130, 0xffff0000, v139
	v_max_f32_e32 v130, v130, v130
	v_max_f32_e32 v130, 0x21800000, v130
	v_rcp_f32_e32 v137, v130
	v_pk_mul_f32 v[124:125], v[124:125], v[128:129]
	v_lshlrev_b32_e32 v128, 16, v131
	v_and_b32_e32 v129, 0xffff0000, v131
	s_waitcnt vmcnt(3)
; DI float bf_lo(unsigned u) { return __uint_as_float(u << 16); }
; DI float bf_hi(unsigned u) { return __uint_as_float(u & 0xffff0000u); }
; DI void phase4(const Params& p, unsigned char* smem, int tid) {
;     ...
; #pragma unroll
;             for (int it = 0; it < 4; ++it)
; #pragma unroll
;                 for (int jt = 0; jt < 2; ++jt)
; #pragma unroll
;                     for (int gp = 0; gp < 2; ++gp) {
;                         const u32x4 a4 = *(const u32x4*)(ga + ((it * 2 + jt) * 2 + gp) * 1024), b4 = *(const u32x4*)(gb + ((it * 2 + jt) * 2 + gp) * 1024);
; #pragma unroll
;                         for (int e = 0; e < 4; ++e) {
;                             acc[it][jt][8 * gp + 2 * e] *= bf_lo(a4[e]) * __builtin_amdgcn_rcpf(fmaxf(bf_lo(b4[e]), 8.6736174e-19f));
;                             acc[it][jt][8 * gp + 2 * e + 1] *= bf_hi(a4[e]) * __builtin_amdgcn_rcpf(fmaxf(bf_hi(b4[e]), 8.6736174e-19f));
;                         }
;                     }
	v_lshlrev_b32_e32 v130, 16, v148
	v_and_b32_e32 v131, 0xffff0000, v148
	v_max_f32_e32 v130, v130, v130
	v_max_f32_e32 v131, v131, v131
	v_max_f32_e32 v130, 0x21800000, v130
	v_max_f32_e32 v131, 0x21800000, v131
	v_rcp_f32_e32 v130, v130
	v_rcp_f32_e32 v131, v131
	v_pk_mul_f32 v[128:129], v[136:137], v[128:129]
	global_load_dwordx4 v[136:139], v[154:155], off nt
	v_pk_mul_f32 v[126:127], v[126:127], v[128:129]
	v_lshlrev_b32_e32 v128, 16, v140
	v_and_b32_e32 v129, 0xffff0000, v140
	v_pk_mul_f32 v[128:129], v[130:131], v[128:129]
	v_lshlrev_b32_e32 v130, 16, v149
	v_and_b32_e32 v131, 0xffff0000, v149
	v_max_f32_e32 v130, v130, v130
	v_max_f32_e32 v131, v131, v131
	v_max_f32_e32 v130, 0x21800000, v130
	v_max_f32_e32 v131, 0x21800000, v131
	v_rcp_f32_e32 v130, v130
	v_rcp_f32_e32 v131, v131
	v_rcp_f32_e32 v170, v175
	v_pk_mul_f32 v[0:1], v[0:1], v[128:129]
	v_lshlrev_b32_e32 v128, 16, v141
	v_and_b32_e32 v129, 0xffff0000, v141
	v_pk_mul_f32 v[128:129], v[130:131], v[128:129]
	v_add_co_u32_e32 v130, vcc, s42, v152
	v_pk_mul_f32 v[160:161], v[170:171], v[164:165]
	s_nop 0
	v_addc_co_u32_e32 v131, vcc, 0, v153, vcc
	v_pk_mul_f32 v[120:121], v[120:121], v[160:161]
	global_load_dwordx4 v[160:163], v[130:131], off offset:-4096 nt
	v_pk_mul_f32 v[2:3], v[2:3], v[128:129]
	v_lshlrev_b32_e32 v128, 16, v150
	v_and_b32_e32 v129, 0xffff0000, v150
	v_max_f32_e32 v128, v128, v128
	v_max_f32_e32 v129, v129, v129
	v_max_f32_e32 v128, 0x21800000, v128
	v_max_f32_e32 v129, 0x21800000, v129
	v_rcp_f32_e32 v128, v128
	v_rcp_f32_e32 v129, v129
	v_lshlrev_b32_e32 v140, 16, v142
	v_and_b32_e32 v141, 0xffff0000, v142
	v_add_co_u32_e32 v156, vcc, s40, v152
	v_pk_mul_f32 v[128:129], v[128:129], v[140:141]
	v_lshlrev_b32_e32 v140, 16, v151
	v_and_b32_e32 v141, 0xffff0000, v151
	v_max_f32_e32 v140, v140, v140
	v_max_f32_e32 v141, v141, v141
	v_max_f32_e32 v140, 0x21800000, v140
	v_max_f32_e32 v141, 0x21800000, v141
	s_waitcnt vmcnt(3)
	v_lshlrev_b32_e32 v148, 16, v132
	v_and_b32_e32 v132, 0xffff0000, v132
	v_rcp_f32_e32 v140, v140
	v_rcp_f32_e32 v141, v141
	v_max_f32_e32 v148, v148, v148
	v_max_f32_e32 v132, v132, v132
	v_max_f32_e32 v148, 0x21800000, v148
	v_max_f32_e32 v132, 0x21800000, v132
	v_rcp_f32_e32 v148, v148
	v_rcp_f32_e32 v149, v132
	v_pk_mul_f32 v[4:5], v[4:5], v[128:129]
	v_lshlrev_b32_e32 v128, 16, v143
	v_and_b32_e32 v129, 0xffff0000, v143
	v_pk_mul_f32 v[128:129], v[140:141], v[128:129]
	v_addc_co_u32_e32 v157, vcc, 0, v153, vcc
	v_pk_mul_f32 v[6:7], v[6:7], v[128:129]
	s_waitcnt vmcnt(2)
	v_lshlrev_b32_e32 v128, 16, v144
	v_and_b32_e32 v129, 0xffff0000, v144
	v_pk_mul_f32 v[128:129], v[148:149], v[128:129]
	global_load_dwordx4 v[148:151], v[154:155], off offset:1024 nt
	global_load_dwordx4 v[140:143], v[156:157], off offset:1024 nt
	global_load_dwordx4 v[164:167], v[156:157], off offset:2048 nt
	v_lshlrev_b32_e32 v132, 16, v133
	v_and_b32_e32 v133, 0xffff0000, v133
	v_max_f32_e32 v132, v132, v132
	v_max_f32_e32 v133, v133, v133
	v_max_f32_e32 v132, 0x21800000, v132
	v_max_f32_e32 v133, 0x21800000, v133
	v_rcp_f32_e32 v132, v132
	v_rcp_f32_e32 v133, v133
	v_pk_mul_f32 v[8:9], v[8:9], v[128:129]
	v_lshlrev_b32_e32 v128, 16, v145
	v_and_b32_e32 v129, 0xffff0000, v145
	v_pk_mul_f32 v[128:129], v[132:133], v[128:129]
	v_lshlrev_b32_e32 v132, 16, v134
	v_and_b32_e32 v133, 0xffff0000, v134
	v_max_f32_e32 v132, v132, v132
	v_max_f32_e32 v133, v133, v133
	v_max_f32_e32 v132, 0x21800000, v132
	v_max_f32_e32 v133, 0x21800000, v133
	v_rcp_f32_e32 v132, v132
	v_rcp_f32_e32 v133, v133
	v_pk_mul_f32 v[10:11], v[10:11], v[128:129]
	v_lshlrev_b32_e32 v128, 16, v146
	v_and_b32_e32 v129, 0xffff0000, v146
	v_pk_mul_f32 v[128:129], v[132:133], v[128:129]
	v_lshlrev_b32_e32 v132, 16, v135
	v_and_b32_e32 v133, 0xffff0000, v135
	v_max_f32_e32 v132, v132, v132
	v_max_f32_e32 v133, v133, v133
	v_max_f32_e32 v132, 0x21800000, v132
	v_max_f32_e32 v133, 0x21800000, v133
	v_rcp_f32_e32 v132, v132
	v_rcp_f32_e32 v133, v133
	v_pk_mul_f32 v[12:13], v[12:13], v[128:129]
	v_lshlrev_b32_e32 v128, 16, v147
	v_and_b32_e32 v129, 0xffff0000, v147
	v_pk_mul_f32 v[128:129], v[132:133], v[128:129]
	s_waitcnt vmcnt(3)
	v_lshlrev_b32_e32 v144, 16, v160
	v_pk_mul_f32 v[14:15], v[14:15], v[128:129]
	v_lshlrev_b32_e32 v128, 16, v136
	v_and_b32_e32 v129, 0xffff0000, v136
	v_max_f32_e32 v128, v128, v128
	v_max_f32_e32 v129, v129, v129
	v_max_f32_e32 v128, 0x21800000, v128
	v_max_f32_e32 v129, 0x21800000, v129
	v_rcp_f32_e32 v128, v128
	v_rcp_f32_e32 v129, v129
	v_and_b32_e32 v145, 0xffff0000, v160
	v_lshlrev_b32_e32 v136, 16, v137
	v_and_b32_e32 v137, 0xffff0000, v137
	v_pk_mul_f32 v[128:129], v[128:129], v[144:145]
	global_load_dwordx4 v[144:147], v[154:155], off offset:2048 nt
	v_max_f32_e32 v136, v136, v136
	v_max_f32_e32 v137, v137, v137
	v_max_f32_e32 v136, 0x21800000, v136
	v_max_f32_e32 v137, 0x21800000, v137
	v_rcp_f32_e32 v136, v136
	v_rcp_f32_e32 v137, v137
	v_pk_mul_f32 v[96:97], v[96:97], v[128:129]
	v_lshlrev_b32_e32 v128, 16, v161
	v_and_b32_e32 v129, 0xffff0000, v161
	v_pk_mul_f32 v[128:129], v[136:137], v[128:129]
	v_lshlrev_b32_e32 v136, 16, v138
	v_and_b32_e32 v137, 0xffff0000, v138
	v_max_f32_e32 v136, v136, v136
	v_max_f32_e32 v137, v137, v137
	v_max_f32_e32 v136, 0x21800000, v136
	v_max_f32_e32 v137, 0x21800000, v137
	v_rcp_f32_e32 v136, v136
	v_rcp_f32_e32 v137, v137
	v_pk_mul_f32 v[98:99], v[98:99], v[128:129]
	v_lshlrev_b32_e32 v128, 16, v162
	v_and_b32_e32 v129, 0xffff0000, v162
	v_pk_mul_f32 v[128:129], v[136:137], v[128:129]
	v_lshlrev_b32_e32 v136, 16, v139
	v_and_b32_e32 v137, 0xffff0000, v139
	v_max_f32_e32 v136, v136, v136
	v_max_f32_e32 v137, v137, v137
	v_max_f32_e32 v136, 0x21800000, v136
	v_max_f32_e32 v137, 0x21800000, v137
	v_rcp_f32_e32 v136, v136
	v_rcp_f32_e32 v137, v137
	v_pk_mul_f32 v[100:101], v[100:101], v[128:129]
	v_lshlrev_b32_e32 v128, 16, v163
	v_and_b32_e32 v129, 0xffff0000, v163
	v_pk_mul_f32 v[128:129], v[136:137], v[128:129]
	s_waitcnt vmcnt(3)
; DI float bf_lo(unsigned u) { return __uint_as_float(u << 16); }
; DI float bf_hi(unsigned u) { return __uint_as_float(u & 0xffff0000u); }
; DI void phase4(const Params& p, unsigned char* smem, int tid) {
;     ...
; #pragma unroll
;             for (int it = 0; it < 4; ++it)
; #pragma unroll
;                 for (int jt = 0; jt < 2; ++jt)
; #pragma unroll
;                     for (int gp = 0; gp < 2; ++gp) {
;                         const u32x4 a4 = *(const u32x4*)(ga + ((it * 2 + jt) * 2 + gp) * 1024), b4 = *(const u32x4*)(gb + ((it * 2 + jt) * 2 + gp) * 1024);
; #pragma unroll
;                         for (int e = 0; e < 4; ++e) {
;                             acc[it][jt][8 * gp + 2 * e] *= bf_lo(a4[e]) * __builtin_amdgcn_rcpf(fmaxf(bf_lo(b4[e]), 8.6736174e-19f));
;                             acc[it][jt][8 * gp + 2 * e + 1] *= bf_hi(a4[e]) * __builtin_amdgcn_rcpf(fmaxf(bf_hi(b4[e]), 8.6736174e-19f));
;                         }
;                     }
	v_lshlrev_b32_e32 v136, 16, v148
	v_and_b32_e32 v137, 0xffff0000, v148
	v_max_f32_e32 v136, v136, v136
	v_max_f32_e32 v137, v137, v137
	v_max_f32_e32 v136, 0x21800000, v136
	v_max_f32_e32 v137, 0x21800000, v137
	v_rcp_f32_e32 v136, v136
	v_rcp_f32_e32 v137, v137
	v_pk_mul_f32 v[102:103], v[102:103], v[128:129]
	s_waitcnt vmcnt(2)
	v_lshlrev_b32_e32 v128, 16, v140
	v_and_b32_e32 v129, 0xffff0000, v140
	v_pk_mul_f32 v[128:129], v[136:137], v[128:129]
	global_load_dwordx4 v[136:139], v[154:155], off offset:3072 nt
	v_pk_mul_f32 v[104:105], v[104:105], v[128:129]
	global_load_dwordx4 v[154:157], v[156:157], off offset:3072 nt
	v_lshlrev_b32_e32 v128, 16, v149
	v_and_b32_e32 v129, 0xffff0000, v149
	v_max_f32_e32 v128, v128, v128
	v_max_f32_e32 v129, v129, v129
	v_max_f32_e32 v128, 0x21800000, v128
	v_max_f32_e32 v129, 0x21800000, v129
	v_rcp_f32_e32 v128, v128
	v_rcp_f32_e32 v129, v129
	v_lshlrev_b32_e32 v140, 16, v141
	v_and_b32_e32 v141, 0xffff0000, v141
	global_load_dwordx4 v[132:135], v[130:131], off nt
	v_pk_mul_f32 v[128:129], v[128:129], v[140:141]
	v_lshlrev_b32_e32 v140, 16, v150
	v_and_b32_e32 v141, 0xffff0000, v150
	v_max_f32_e32 v140, v140, v140
	v_max_f32_e32 v141, v141, v141
	v_max_f32_e32 v140, 0x21800000, v140
	v_max_f32_e32 v141, 0x21800000, v141
	v_rcp_f32_e32 v140, v140
	v_rcp_f32_e32 v141, v141
	v_pk_mul_f32 v[106:107], v[106:107], v[128:129]
	v_lshlrev_b32_e32 v128, 16, v142
	v_and_b32_e32 v129, 0xffff0000, v142
	v_pk_mul_f32 v[128:129], v[140:141], v[128:129]
	v_lshlrev_b32_e32 v140, 16, v151
	v_and_b32_e32 v141, 0xffff0000, v151
	v_max_f32_e32 v140, v140, v140
	v_max_f32_e32 v141, v141, v141
	v_max_f32_e32 v140, 0x21800000, v140
	v_max_f32_e32 v141, 0x21800000, v141
	v_rcp_f32_e32 v140, v140
	v_rcp_f32_e32 v141, v141
	v_pk_mul_f32 v[108:109], v[108:109], v[128:129]
	v_lshlrev_b32_e32 v128, 16, v143
	v_and_b32_e32 v129, 0xffff0000, v143
	v_pk_mul_f32 v[128:129], v[140:141], v[128:129]
	s_waitcnt vmcnt(3)
	v_lshlrev_b32_e32 v140, 16, v144
	v_and_b32_e32 v141, 0xffff0000, v144
	v_max_f32_e32 v140, v140, v140
	v_max_f32_e32 v141, v141, v141
	v_max_f32_e32 v140, 0x21800000, v140
	v_max_f32_e32 v141, 0x21800000, v141
	v_rcp_f32_e32 v140, v140
	v_rcp_f32_e32 v141, v141
	v_pk_mul_f32 v[110:111], v[110:111], v[128:129]
	v_lshlrev_b32_e32 v128, 16, v164
	v_and_b32_e32 v129, 0xffff0000, v164
	v_pk_mul_f32 v[128:129], v[140:141], v[128:129]
	v_lshlrev_b32_e32 v140, 16, v145
	v_and_b32_e32 v141, 0xffff0000, v145
	v_max_f32_e32 v140, v140, v140
	v_max_f32_e32 v141, v141, v141
	v_max_f32_e32 v140, 0x21800000, v140
	v_max_f32_e32 v141, 0x21800000, v141
	v_rcp_f32_e32 v140, v140
	v_rcp_f32_e32 v141, v141
	v_pk_mul_f32 v[32:33], v[32:33], v[128:129]
	v_lshlrev_b32_e32 v128, 16, v165
	v_and_b32_e32 v129, 0xffff0000, v165
	v_pk_mul_f32 v[144:145], v[140:141], v[128:129]
	v_add_co_u32_e32 v128, vcc, s45, v152
	v_lshlrev_b32_e32 v148, 16, v146
	s_nop 0
	v_addc_co_u32_e32 v129, vcc, 0, v153, vcc
	global_load_dwordx4 v[140:143], v[128:129], off offset:-4096 nt
	v_and_b32_e32 v146, 0xffff0000, v146
	v_max_f32_e32 v146, v146, v146
	v_max_f32_e32 v148, v148, v148
	v_max_f32_e32 v146, 0x21800000, v146
	v_max_f32_e32 v148, 0x21800000, v148
	v_rcp_f32_e32 v149, v146
	v_lshlrev_b32_e32 v146, 16, v147
	v_and_b32_e32 v147, 0xffff0000, v147
	v_rcp_f32_e32 v148, v148
	v_max_f32_e32 v146, v146, v146
	v_max_f32_e32 v147, v147, v147
	v_max_f32_e32 v146, 0x21800000, v146
	v_max_f32_e32 v147, 0x21800000, v147
	v_rcp_f32_e32 v146, v146
	v_rcp_f32_e32 v147, v147
	v_pk_mul_f32 v[34:35], v[34:35], v[144:145]
	v_lshlrev_b32_e32 v144, 16, v166
	v_and_b32_e32 v145, 0xffff0000, v166
	v_pk_mul_f32 v[144:145], v[148:149], v[144:145]
	v_add_co_u32_e32 v160, vcc, s43, v152
	v_pk_mul_f32 v[36:37], v[36:37], v[144:145]
	v_lshlrev_b32_e32 v144, 16, v167
	v_and_b32_e32 v145, 0xffff0000, v167
	v_pk_mul_f32 v[144:145], v[146:147], v[144:145]
	s_waitcnt vmcnt(3)
	v_lshlrev_b32_e32 v146, 16, v136
	v_and_b32_e32 v136, 0xffff0000, v136
	v_max_f32_e32 v146, v146, v146
	v_max_f32_e32 v136, v136, v136
	v_max_f32_e32 v146, 0x21800000, v146
	v_max_f32_e32 v136, 0x21800000, v136
	v_rcp_f32_e32 v146, v146
	v_rcp_f32_e32 v147, v136
	v_lshlrev_b32_e32 v136, 16, v137
	v_and_b32_e32 v137, 0xffff0000, v137
	v_max_f32_e32 v136, v136, v136
	v_max_f32_e32 v137, v137, v137
	v_pk_mul_f32 v[38:39], v[38:39], v[144:145]
	s_waitcnt vmcnt(2)
	v_lshlrev_b32_e32 v144, 16, v154
	v_and_b32_e32 v145, 0xffff0000, v154
	v_max_f32_e32 v136, 0x21800000, v136
	v_max_f32_e32 v137, 0x21800000, v137
	v_pk_mul_f32 v[144:145], v[146:147], v[144:145]
	v_rcp_f32_e32 v136, v136
	v_rcp_f32_e32 v137, v137
	v_addc_co_u32_e32 v161, vcc, 0, v153, vcc
	v_pk_mul_f32 v[40:41], v[40:41], v[144:145]
	global_load_dwordx4 v[144:147], v[160:161], off offset:1024 nt
	v_lshlrev_b32_e32 v148, 16, v155
	v_and_b32_e32 v149, 0xffff0000, v155
	v_pk_mul_f32 v[136:137], v[136:137], v[148:149]
	v_lshlrev_b32_e32 v148, 16, v138
	v_max_f32_e32 v148, v148, v148
	v_max_f32_e32 v148, 0x21800000, v148
	v_rcp_f32_e32 v152, v148
	global_load_dwordx4 v[148:151], v[130:131], off offset:1024 nt
	v_and_b32_e32 v138, 0xffff0000, v138
	v_max_f32_e32 v138, v138, v138
	v_max_f32_e32 v138, 0x21800000, v138
	v_rcp_f32_e32 v153, v138
	v_lshlrev_b32_e32 v138, 16, v139
	v_and_b32_e32 v139, 0xffff0000, v139
	v_max_f32_e32 v138, v138, v138
	v_max_f32_e32 v139, v139, v139
	v_max_f32_e32 v138, 0x21800000, v138
	v_max_f32_e32 v139, 0x21800000, v139
	v_rcp_f32_e32 v138, v138
	v_rcp_f32_e32 v139, v139
	v_pk_mul_f32 v[42:43], v[42:43], v[136:137]
	v_lshlrev_b32_e32 v136, 16, v156
	v_and_b32_e32 v137, 0xffff0000, v156
	v_pk_mul_f32 v[136:137], v[152:153], v[136:137]
	s_waitcnt vmcnt(2)
; DI float bf_lo(unsigned u) { return __uint_as_float(u << 16); }
; DI float bf_hi(unsigned u) { return __uint_as_float(u & 0xffff0000u); }
; DI void phase4(const Params& p, unsigned char* smem, int tid) {
;     ...
; #pragma unroll
;             for (int it = 0; it < 4; ++it)
; #pragma unroll
;                 for (int jt = 0; jt < 2; ++jt)
; #pragma unroll
;                     for (int gp = 0; gp < 2; ++gp) {
;                         const u32x4 a4 = *(const u32x4*)(ga + ((it * 2 + jt) * 2 + gp) * 1024), b4 = *(const u32x4*)(gb + ((it * 2 + jt) * 2 + gp) * 1024);
; #pragma unroll
;                         for (int e = 0; e < 4; ++e) {
;                             acc[it][jt][8 * gp + 2 * e] *= bf_lo(a4[e]) * __builtin_amdgcn_rcpf(fmaxf(bf_lo(b4[e]), 8.6736174e-19f));
;                             acc[it][jt][8 * gp + 2 * e + 1] *= bf_hi(a4[e]) * __builtin_amdgcn_rcpf(fmaxf(bf_hi(b4[e]), 8.6736174e-19f));
;                         }
;                     }
	v_lshlrev_b32_e32 v154, 16, v140
	v_pk_mul_f32 v[44:45], v[44:45], v[136:137]
	v_lshlrev_b32_e32 v136, 16, v157
	v_and_b32_e32 v137, 0xffff0000, v157
	v_pk_mul_f32 v[152:153], v[138:139], v[136:137]
	v_and_b32_e32 v140, 0xffff0000, v140
	v_pk_mul_f32 v[46:47], v[46:47], v[152:153]
	v_lshlrev_b32_e32 v152, 16, v132
	v_and_b32_e32 v153, 0xffff0000, v132
	v_lshlrev_b32_e32 v132, 16, v141
	v_max_f32_e32 v140, v140, v140
	v_max_f32_e32 v132, v132, v132
	v_max_f32_e32 v140, 0x21800000, v140
	v_max_f32_e32 v132, 0x21800000, v132
	v_max_f32_e32 v154, v154, v154
	v_rcp_f32_e32 v155, v140
	v_rcp_f32_e32 v140, v132
	v_and_b32_e32 v132, 0xffff0000, v141
	v_max_f32_e32 v154, 0x21800000, v154
	v_max_f32_e32 v132, v132, v132
	v_rcp_f32_e32 v154, v154
	v_max_f32_e32 v132, 0x21800000, v132
	v_rcp_f32_e32 v141, v132
	v_lshlrev_b32_e32 v132, 16, v133
	v_pk_mul_f32 v[156:157], v[154:155], v[152:153]
	global_load_dwordx4 v[152:155], v[160:161], off offset:2048 nt
	v_and_b32_e32 v133, 0xffff0000, v133
	v_pk_mul_f32 v[140:141], v[140:141], v[132:133]
	v_lshlrev_b32_e32 v132, 16, v142
	v_max_f32_e32 v132, v132, v132
	global_load_dwordx4 v[136:139], v[130:131], off offset:3072 nt
	v_pk_mul_f32 v[80:81], v[80:81], v[156:157]
	v_max_f32_e32 v156, 0x21800000, v132
	global_load_dwordx4 v[130:133], v[130:131], off offset:2048 nt
	v_and_b32_e32 v142, 0xffff0000, v142
	v_max_f32_e32 v142, v142, v142
	v_max_f32_e32 v142, 0x21800000, v142
	v_rcp_f32_e32 v156, v156
	v_rcp_f32_e32 v157, v142
	v_pk_mul_f32 v[82:83], v[82:83], v[140:141]
	v_lshlrev_b32_e32 v140, 16, v134
	v_and_b32_e32 v141, 0xffff0000, v134
	v_lshlrev_b32_e32 v134, 16, v143
	v_max_f32_e32 v134, v134, v134
	v_max_f32_e32 v134, 0x21800000, v134
	v_rcp_f32_e32 v142, v134
	v_and_b32_e32 v134, 0xffff0000, v143
	v_pk_mul_f32 v[140:141], v[156:157], v[140:141]
	v_max_f32_e32 v134, v134, v134
	v_max_f32_e32 v134, 0x21800000, v134
	v_pk_mul_f32 v[84:85], v[84:85], v[140:141]
	s_waitcnt vmcnt(4)
	v_lshlrev_b32_e32 v140, 16, v144
	v_and_b32_e32 v141, 0xffff0000, v144
	v_rcp_f32_e32 v143, v134
	v_max_f32_e32 v140, v140, v140
	v_max_f32_e32 v141, v141, v141
	v_max_f32_e32 v140, 0x21800000, v140
	v_max_f32_e32 v141, 0x21800000, v141
	v_rcp_f32_e32 v140, v140
	v_rcp_f32_e32 v141, v141
	v_lshlrev_b32_e32 v134, 16, v135
	v_and_b32_e32 v135, 0xffff0000, v135
	v_pk_mul_f32 v[134:135], v[142:143], v[134:135]
	s_nop 0
	v_pk_mul_f32 v[86:87], v[86:87], v[134:135]
	s_waitcnt vmcnt(3)
	v_lshlrev_b32_e32 v134, 16, v148
	v_and_b32_e32 v135, 0xffff0000, v148
	v_pk_mul_f32 v[134:135], v[140:141], v[134:135]
	v_lshlrev_b32_e32 v140, 16, v145
	v_max_f32_e32 v140, v140, v140
	v_max_f32_e32 v140, 0x21800000, v140
	v_rcp_f32_e32 v144, v140
	v_and_b32_e32 v140, 0xffff0000, v145
	v_max_f32_e32 v140, v140, v140
	v_max_f32_e32 v145, 0x21800000, v140
	global_load_dwordx4 v[140:143], v[160:161], off offset:3072 nt
	v_rcp_f32_e32 v145, v145
	v_pk_mul_f32 v[88:89], v[88:89], v[134:135]
	v_lshlrev_b32_e32 v134, 16, v149
	v_and_b32_e32 v135, 0xffff0000, v149
	v_pk_mul_f32 v[134:135], v[144:145], v[134:135]
	v_lshlrev_b32_e32 v144, 16, v146
	v_and_b32_e32 v145, 0xffff0000, v146
	v_max_f32_e32 v144, v144, v144
	v_max_f32_e32 v145, v145, v145
	v_max_f32_e32 v144, 0x21800000, v144
	v_max_f32_e32 v145, 0x21800000, v145
	v_rcp_f32_e32 v144, v144
	v_rcp_f32_e32 v145, v145
	v_pk_mul_f32 v[90:91], v[90:91], v[134:135]
	v_lshlrev_b32_e32 v134, 16, v150
	v_and_b32_e32 v135, 0xffff0000, v150
	v_pk_mul_f32 v[134:135], v[144:145], v[134:135]
	v_lshlrev_b32_e32 v144, 16, v147
	v_and_b32_e32 v145, 0xffff0000, v147
	v_max_f32_e32 v144, v144, v144
	v_max_f32_e32 v145, v145, v145
	v_max_f32_e32 v144, 0x21800000, v144
	v_max_f32_e32 v145, 0x21800000, v145
	v_rcp_f32_e32 v144, v144
	v_rcp_f32_e32 v145, v145
	v_pk_mul_f32 v[92:93], v[92:93], v[134:135]
	v_lshlrev_b32_e32 v134, 16, v151
	v_and_b32_e32 v135, 0xffff0000, v151
	v_pk_mul_f32 v[134:135], v[144:145], v[134:135]
	s_waitcnt vmcnt(3)
	v_lshlrev_b32_e32 v144, 16, v152
	v_and_b32_e32 v145, 0xffff0000, v152
	v_max_f32_e32 v144, v144, v144
	v_max_f32_e32 v145, v145, v145
	v_max_f32_e32 v144, 0x21800000, v144
	v_max_f32_e32 v145, 0x21800000, v145
	v_rcp_f32_e32 v144, v144
	v_rcp_f32_e32 v145, v145
	v_pk_mul_f32 v[94:95], v[94:95], v[134:135]
	s_waitcnt vmcnt(1)
	v_lshlrev_b32_e32 v134, 16, v130
	v_and_b32_e32 v135, 0xffff0000, v130
	v_lshlrev_b32_e32 v130, 16, v153
	v_max_f32_e32 v130, v130, v130
	v_max_f32_e32 v130, 0x21800000, v130
	v_rcp_f32_e32 v148, v130
	v_and_b32_e32 v130, 0xffff0000, v153
	v_pk_mul_f32 v[134:135], v[144:145], v[134:135]
	v_max_f32_e32 v130, v130, v130
	global_load_dwordx4 v[144:147], v[128:129], off nt
	v_max_f32_e32 v130, 0x21800000, v130
	v_rcp_f32_e32 v149, v130
	v_lshlrev_b32_e32 v130, 16, v131
	v_and_b32_e32 v131, 0xffff0000, v131
	v_pk_mul_f32 v[48:49], v[48:49], v[134:135]
	v_pk_mul_f32 v[130:131], v[148:149], v[130:131]
	v_lshlrev_b32_e32 v134, 16, v154
	global_load_dwordx4 v[148:151], v[158:159], off nt
	v_and_b32_e32 v135, 0xffff0000, v154
	v_max_f32_e32 v134, v134, v134
	v_max_f32_e32 v135, v135, v135
	v_max_f32_e32 v134, 0x21800000, v134
	v_max_f32_e32 v135, 0x21800000, v135
	v_rcp_f32_e32 v134, v134
	v_rcp_f32_e32 v135, v135
	v_pk_mul_f32 v[50:51], v[50:51], v[130:131]
	v_lshlrev_b32_e32 v130, 16, v132
	v_and_b32_e32 v131, 0xffff0000, v132
	v_lshlrev_b32_e32 v132, 16, v155
	v_max_f32_e32 v132, v132, v132
	v_max_f32_e32 v132, 0x21800000, v132
	v_pk_mul_f32 v[130:131], v[134:135], v[130:131]
	v_rcp_f32_e32 v134, v132
	v_and_b32_e32 v132, 0xffff0000, v155
	v_max_f32_e32 v132, v132, v132
	v_max_f32_e32 v132, 0x21800000, v132
	v_rcp_f32_e32 v135, v132
	v_pk_mul_f32 v[52:53], v[52:53], v[130:131]
	v_lshlrev_b32_e32 v130, 16, v133
	v_and_b32_e32 v131, 0xffff0000, v133
	v_pk_mul_f32 v[130:131], v[134:135], v[130:131]
	s_waitcnt vmcnt(2)
; DI float bf_lo(unsigned u) { return __uint_as_float(u << 16); }
; DI float bf_hi(unsigned u) { return __uint_as_float(u & 0xffff0000u); }
; DI void phase4(const Params& p, unsigned char* smem, int tid) {
;     ...
; #pragma unroll
;             for (int it = 0; it < 4; ++it)
; #pragma unroll
;                 for (int jt = 0; jt < 2; ++jt)
; #pragma unroll
;                     for (int gp = 0; gp < 2; ++gp) {
;                         const u32x4 a4 = *(const u32x4*)(ga + ((it * 2 + jt) * 2 + gp) * 1024), b4 = *(const u32x4*)(gb + ((it * 2 + jt) * 2 + gp) * 1024);
; #pragma unroll
;                         for (int e = 0; e < 4; ++e) {
;                             acc[it][jt][8 * gp + 2 * e] *= bf_lo(a4[e]) * __builtin_amdgcn_rcpf(fmaxf(bf_lo(b4[e]), 8.6736174e-19f));
;                             acc[it][jt][8 * gp + 2 * e + 1] *= bf_hi(a4[e]) * __builtin_amdgcn_rcpf(fmaxf(bf_hi(b4[e]), 8.6736174e-19f));
;                         }
;                     }
	v_lshlrev_b32_e32 v132, 16, v140
	v_and_b32_e32 v133, 0xffff0000, v140
	v_max_f32_e32 v132, v132, v132
	v_max_f32_e32 v133, v133, v133
	v_max_f32_e32 v132, 0x21800000, v132
	v_max_f32_e32 v133, 0x21800000, v133
	v_rcp_f32_e32 v132, v132
	v_rcp_f32_e32 v133, v133
	v_pk_mul_f32 v[54:55], v[54:55], v[130:131]
	v_lshlrev_b32_e32 v130, 16, v136
	v_and_b32_e32 v131, 0xffff0000, v136
	v_pk_mul_f32 v[134:135], v[132:133], v[130:131]
	v_lshlrev_b32_e32 v130, 16, v141
	v_max_f32_e32 v130, v130, v130
	v_max_f32_e32 v130, 0x21800000, v130
	v_rcp_f32_e32 v140, v130
	v_and_b32_e32 v130, 0xffff0000, v141
	v_max_f32_e32 v130, v130, v130
	v_max_f32_e32 v130, 0x21800000, v130
	v_rcp_f32_e32 v141, v130
	global_load_dwordx4 v[130:133], v[128:129], off offset:1024 nt
	v_pk_mul_f32 v[56:57], v[56:57], v[134:135]
	v_lshlrev_b32_e32 v134, 16, v137
	v_and_b32_e32 v135, 0xffff0000, v137
	v_pk_mul_f32 v[140:141], v[140:141], v[134:135]
	v_lshlrev_b32_e32 v134, 16, v142
	v_max_f32_e32 v134, v134, v134
	v_max_f32_e32 v134, 0x21800000, v134
	v_rcp_f32_e32 v152, v134
	global_load_dwordx4 v[134:137], v[158:159], off offset:1024 nt
	v_and_b32_e32 v142, 0xffff0000, v142
	v_max_f32_e32 v142, v142, v142
	v_max_f32_e32 v142, 0x21800000, v142
	v_rcp_f32_e32 v153, v142
	v_pk_mul_f32 v[58:59], v[58:59], v[140:141]
	v_lshlrev_b32_e32 v140, 16, v138
	v_and_b32_e32 v141, 0xffff0000, v138
	v_lshlrev_b32_e32 v138, 16, v143
	v_max_f32_e32 v138, v138, v138
	v_max_f32_e32 v138, 0x21800000, v138
	v_rcp_f32_e32 v142, v138
	v_and_b32_e32 v138, 0xffff0000, v143
	v_pk_mul_f32 v[140:141], v[152:153], v[140:141]
	v_max_f32_e32 v138, v138, v138
	v_max_f32_e32 v138, 0x21800000, v138
	v_pk_mul_f32 v[60:61], v[60:61], v[140:141]
	v_rcp_f32_e32 v143, v138
	v_lshlrev_b32_e32 v138, 16, v139
	s_waitcnt vmcnt(3)
	v_lshlrev_b32_e32 v140, 16, v144
	v_and_b32_e32 v141, 0xffff0000, v144
	v_max_f32_e32 v140, v140, v140
	v_max_f32_e32 v141, v141, v141
	v_max_f32_e32 v140, 0x21800000, v140
	v_max_f32_e32 v141, 0x21800000, v141
	v_rcp_f32_e32 v140, v140
	v_rcp_f32_e32 v141, v141
	v_and_b32_e32 v139, 0xffff0000, v139
	v_pk_mul_f32 v[138:139], v[142:143], v[138:139]
	s_nop 0
	v_pk_mul_f32 v[62:63], v[62:63], v[138:139]
	s_waitcnt vmcnt(2)
	v_lshlrev_b32_e32 v138, 16, v148
	v_and_b32_e32 v139, 0xffff0000, v148
	v_pk_mul_f32 v[142:143], v[140:141], v[138:139]
	v_lshlrev_b32_e32 v138, 16, v145
	v_max_f32_e32 v138, v138, v138
	v_max_f32_e32 v138, 0x21800000, v138
	v_rcp_f32_e32 v144, v138
	v_and_b32_e32 v138, 0xffff0000, v145
	v_max_f32_e32 v138, v138, v138
	v_max_f32_e32 v145, 0x21800000, v138
	global_load_dwordx4 v[138:141], v[128:129], off offset:2048 nt
	v_rcp_f32_e32 v145, v145
	v_pk_mul_f32 v[64:65], v[64:65], v[142:143]
	v_lshlrev_b32_e32 v142, 16, v149
	v_and_b32_e32 v143, 0xffff0000, v149
	v_pk_mul_f32 v[148:149], v[144:145], v[142:143]
	v_lshlrev_b32_e32 v142, 16, v146
	v_max_f32_e32 v142, v142, v142
	v_max_f32_e32 v152, 0x21800000, v142
	global_load_dwordx4 v[142:145], v[158:159], off offset:2048 nt
	v_and_b32_e32 v146, 0xffff0000, v146
	v_max_f32_e32 v146, v146, v146
	v_max_f32_e32 v146, 0x21800000, v146
	v_rcp_f32_e32 v153, v146
	v_lshlrev_b32_e32 v146, 16, v147
	v_and_b32_e32 v147, 0xffff0000, v147
	v_rcp_f32_e32 v152, v152
	v_max_f32_e32 v146, v146, v146
	v_max_f32_e32 v147, v147, v147
	v_max_f32_e32 v146, 0x21800000, v146
	v_max_f32_e32 v147, 0x21800000, v147
	v_rcp_f32_e32 v146, v146
	v_rcp_f32_e32 v147, v147
	v_pk_mul_f32 v[66:67], v[66:67], v[148:149]
	v_lshlrev_b32_e32 v148, 16, v150
	v_and_b32_e32 v149, 0xffff0000, v150
	v_pk_mul_f32 v[148:149], v[152:153], v[148:149]
	s_nop 0
	v_pk_mul_f32 v[68:69], v[68:69], v[148:149]
	v_lshlrev_b32_e32 v148, 16, v151
	v_and_b32_e32 v149, 0xffff0000, v151
	v_pk_mul_f32 v[146:147], v[146:147], v[148:149]
	s_waitcnt vmcnt(3)
	v_lshlrev_b32_e32 v148, 16, v130
	v_and_b32_e32 v130, 0xffff0000, v130
	v_max_f32_e32 v148, v148, v148
	v_max_f32_e32 v130, v130, v130
	v_max_f32_e32 v148, 0x21800000, v148
	v_max_f32_e32 v130, 0x21800000, v130
	v_rcp_f32_e32 v148, v148
	v_rcp_f32_e32 v149, v130
	v_lshlrev_b32_e32 v130, 16, v131
	v_max_f32_e32 v130, v130, v130
	v_pk_mul_f32 v[70:71], v[70:71], v[146:147]
	s_waitcnt vmcnt(2)
	v_lshlrev_b32_e32 v146, 16, v134
	v_and_b32_e32 v147, 0xffff0000, v134
	v_max_f32_e32 v130, 0x21800000, v130
	v_pk_mul_f32 v[146:147], v[148:149], v[146:147]
	v_rcp_f32_e32 v148, v130
	v_and_b32_e32 v134, 0xffff0000, v131
	global_load_dwordx4 v[128:131], v[128:129], off offset:3072 nt
	v_max_f32_e32 v134, v134, v134
	v_pk_mul_f32 v[72:73], v[72:73], v[146:147]
	v_lshlrev_b32_e32 v146, 16, v132
	v_and_b32_e32 v132, 0xffff0000, v132
	v_max_f32_e32 v134, 0x21800000, v134
	v_max_f32_e32 v132, v132, v132
	v_rcp_f32_e32 v149, v134
	v_max_f32_e32 v146, v146, v146
	v_max_f32_e32 v132, 0x21800000, v132
	v_max_f32_e32 v146, 0x21800000, v146
	v_rcp_f32_e32 v147, v132
	v_lshlrev_b32_e32 v132, 16, v133
	v_and_b32_e32 v133, 0xffff0000, v133
	v_rcp_f32_e32 v146, v146
	v_max_f32_e32 v132, v132, v132
	v_max_f32_e32 v133, v133, v133
	v_lshlrev_b32_e32 v134, 16, v135
	v_and_b32_e32 v135, 0xffff0000, v135
	v_max_f32_e32 v132, 0x21800000, v132
	v_max_f32_e32 v133, 0x21800000, v133
	v_pk_mul_f32 v[134:135], v[148:149], v[134:135]
	v_rcp_f32_e32 v132, v132
	v_rcp_f32_e32 v133, v133
	v_pk_mul_f32 v[74:75], v[74:75], v[134:135]
	v_lshlrev_b32_e32 v134, 16, v136
	v_and_b32_e32 v135, 0xffff0000, v136
	v_pk_mul_f32 v[134:135], v[146:147], v[134:135]
	s_waitcnt vmcnt(0)
; DI float bf_lo(unsigned u) { return __uint_as_float(u << 16); }
; DI float bf_hi(unsigned u) { return __uint_as_float(u & 0xffff0000u); }
; #define G_LOAD(pr, qr, kt_) if (MODE != 1) { _Pragma("unroll") for (int r = 0; r < NP; ++r) pr[r] = *(const u32x4*)(pp + (size_t)(r * 128) * ldp + (kt_) * BK); \
;                               _Pragma("unroll") for (int r = 0; r < NQ; ++r) qr[r] = *(const u32x4*)(qp + (size_t)(r * 128) * ldq + (kt_) * BK); }
; #define G_STORE(pr, qr, so_) { unsigned char* w_ = wP + (so_); \
;                               _Pragma("unroll") for (int r = 0; r < NP; ++r) *(u32x4*)(w_ + r * 128 * LROW) = pr[r]; \
;                               _Pragma("unroll") for (int r = 0; r < NQ; ++r) *(u32x4*)(w_ + BI * LROW + r * 128 * LROW) = qr[r]; }
; #define G_LOAD(pr, qr, kt_) if (MODE != 1) { _Pragma("unroll") for (int r = 0; r < NP; ++r) pr[r] = *(const u32x4*)(pp + (size_t)(r * 128) * ldp + (kt_) * BK); \
;                               _Pragma("unroll") for (int r = 0; r < NQ; ++r) qr[r] = *(const u32x4*)(qp + (size_t)(r * 128) * ldq + (kt_) * BK); }
; #define G_STORE(pr, qr, so_) { unsigned char* w_ = wP + (so_); \
;                               _Pragma("unroll") for (int r = 0; r < NP; ++r) *(u32x4*)(w_ + r * 128 * LROW) = pr[r]; \
;                               _Pragma("unroll") for (int r = 0; r < NQ; ++r) *(u32x4*)(w_ + BI * LROW + r * 128 * LROW) = qr[r]; }
;     ...
;     G_LOAD(p0, q0, 0)
;     G_LOAD(p1, q1, 1)
;     G_LOAD(p2, q2, 2)
;     G_STORE(p0, q0, 0)
;     G_LOAD(p0, q0, 3)
;     G_STORE(p1, q1, STAGE)
; DI void phase4(const Params& p, unsigned char* smem, int tid) {
;     ...
; #pragma unroll
;             for (int it = 0; it < 4; ++it)
; #pragma unroll
;                 for (int jt = 0; jt < 2; ++jt)
; #pragma unroll
;                     for (int gp = 0; gp < 2; ++gp) {
;                         const u32x4 a4 = *(const u32x4*)(ga + ((it * 2 + jt) * 2 + gp) * 1024), b4 = *(const u32x4*)(gb + ((it * 2 + jt) * 2 + gp) * 1024);
; #pragma unroll
;                         for (int e = 0; e < 4; ++e) {
;                             acc[it][jt][8 * gp + 2 * e] *= bf_lo(a4[e]) * __builtin_amdgcn_rcpf(fmaxf(bf_lo(b4[e]), 8.6736174e-19f));
;                             acc[it][jt][8 * gp + 2 * e + 1] *= bf_hi(a4[e]) * __builtin_amdgcn_rcpf(fmaxf(bf_hi(b4[e]), 8.6736174e-19f));
;                         }
;                     }
	v_lshlrev_b32_e32 v152, 16, v128
	v_pk_mul_f32 v[76:77], v[76:77], v[134:135]
	v_lshlrev_b32_e32 v134, 16, v137
	v_and_b32_e32 v135, 0xffff0000, v137
	v_pk_mul_f32 v[132:133], v[132:133], v[134:135]
	v_lshlrev_b32_e32 v134, 16, v138
	v_and_b32_e32 v135, 0xffff0000, v138
	v_max_f32_e32 v134, v134, v134
	v_max_f32_e32 v135, v135, v135
	v_max_f32_e32 v134, 0x21800000, v134
	v_max_f32_e32 v135, 0x21800000, v135
	v_rcp_f32_e32 v134, v134
	v_rcp_f32_e32 v135, v135
	v_pk_mul_f32 v[78:79], v[78:79], v[132:133]
	v_lshlrev_b32_e32 v132, 16, v142
	v_and_b32_e32 v133, 0xffff0000, v142
	v_pk_mul_f32 v[132:133], v[134:135], v[132:133]
	v_lshlrev_b32_e32 v134, 16, v139
	v_and_b32_e32 v135, 0xffff0000, v139
	v_max_f32_e32 v134, v134, v134
	v_max_f32_e32 v135, v135, v135
	v_max_f32_e32 v134, 0x21800000, v134
	v_max_f32_e32 v135, 0x21800000, v135
	v_rcp_f32_e32 v134, v134
	v_rcp_f32_e32 v135, v135
	v_pk_mul_f32 v[16:17], v[16:17], v[132:133]
	v_lshlrev_b32_e32 v132, 16, v143
	v_and_b32_e32 v133, 0xffff0000, v143
	v_pk_mul_f32 v[132:133], v[134:135], v[132:133]
	v_lshlrev_b32_e32 v134, 16, v140
	v_and_b32_e32 v135, 0xffff0000, v140
	v_max_f32_e32 v134, v134, v134
	v_max_f32_e32 v135, v135, v135
	v_max_f32_e32 v134, 0x21800000, v134
	v_max_f32_e32 v135, 0x21800000, v135
	v_rcp_f32_e32 v134, v134
	v_rcp_f32_e32 v135, v135
	v_pk_mul_f32 v[18:19], v[18:19], v[132:133]
	v_lshlrev_b32_e32 v132, 16, v144
	v_and_b32_e32 v133, 0xffff0000, v144
	v_pk_mul_f32 v[132:133], v[134:135], v[132:133]
	v_lshlrev_b32_e32 v134, 16, v141
	v_and_b32_e32 v135, 0xffff0000, v141
	v_max_f32_e32 v134, v134, v134
	v_max_f32_e32 v135, v135, v135
	v_max_f32_e32 v134, 0x21800000, v134
	v_max_f32_e32 v135, 0x21800000, v135
	v_rcp_f32_e32 v134, v134
	v_rcp_f32_e32 v135, v135
	v_and_b32_e32 v128, 0xffff0000, v128
	v_max_f32_e32 v128, v128, v128
	v_ashrrev_i32_e32 v182, 2, v210
	v_max_f32_e32 v152, v152, v152
	v_max_f32_e32 v128, 0x21800000, v128
	v_pk_mul_f32 v[20:21], v[20:21], v[132:133]
	v_lshlrev_b32_e32 v132, 16, v145
	v_and_b32_e32 v133, 0xffff0000, v145
	v_ashrrev_i32_e32 v183, 31, v182
	v_max_f32_e32 v152, 0x21800000, v152
	v_rcp_f32_e32 v153, v128
	v_lshlrev_b32_e32 v128, 16, v129
	v_and_b32_e32 v129, 0xffff0000, v129
	v_pk_mul_f32 v[148:149], v[134:135], v[132:133]
	v_lshlrev_b64 v[190:191], 11, v[182:183]
	v_lshlrev_b32_e32 v134, 4, v210
	v_rcp_f32_e32 v152, v152
	v_max_f32_e32 v128, v128, v128
	v_max_f32_e32 v129, v129, v129
	v_lshl_add_u64 v[132:133], s[58:59], 0, v[190:191]
	s_mov_b64 s[98:99], s[58:59]
	v_and_b32_e32 v212, 48, v134
	v_max_f32_e32 v128, 0x21800000, v128
	v_max_f32_e32 v129, 0x21800000, v129
	v_lshl_add_u64 v[184:185], v[132:133], 0, v[212:213]
	v_add_u32_e32 v250, v190, v212
	v_add_u32_e32 v251, 0x40000, v250
	v_rcp_f32_e32 v128, v128
	v_rcp_f32_e32 v129, v129
	v_lshl_add_u64 v[140:141], s[18:19], 0, v[190:191]
	s_mov_b64 s[100:101], s[18:19]
	v_add_co_u32_e32 v150, vcc, s34, v184
	v_pk_mul_f32 v[22:23], v[22:23], v[148:149]
	v_lshlrev_b32_e32 v148, 16, v178
	v_and_b32_e32 v149, 0xffff0000, v178
	v_addc_co_u32_e32 v151, vcc, 0, v185, vcc
	v_lshl_add_u64 v[186:187], v[140:141], 0, v[212:213]
	v_pk_mul_f32 v[148:149], v[152:153], v[148:149]
	v_add_co_u32_e32 v188, vcc, s34, v186
	v_pk_mul_f32 v[24:25], v[24:25], v[148:149]
	v_lshlrev_b32_e32 v148, 16, v179
	v_and_b32_e32 v149, 0xffff0000, v179
	v_addc_co_u32_e32 v189, vcc, 0, v187, vcc
	v_pk_mul_f32 v[128:129], v[128:129], v[148:149]
	v_lshlrev_b32_e32 v148, 16, v130
	global_load_dwordx4 v[132:135], v[184:185], off
	global_load_dwordx4 v[136:139], v[150:151], off
	global_load_dwordx4 v[140:143], v[186:187], off
	global_load_dwordx4 v[144:147], v[188:189], off
	global_load_dwordx4 v[192:195], v[184:185], off offset:64
	global_load_dwordx4 v[196:199], v[150:151], off offset:64
	global_load_dwordx4 v[200:203], v[186:187], off offset:64
	v_max_f32_e32 v148, v148, v148
	global_load_dwordx4 v[204:207], v[188:189], off offset:64
	v_max_f32_e32 v148, 0x21800000, v148
	v_rcp_f32_e32 v208, v148
	global_load_dwordx4 v[176:179], v[184:185], off offset:128
	global_load_dwordx4 v[160:163], v[184:185], off offset:192
	global_load_dwordx4 v[172:175], v[150:151], off offset:128
	global_load_dwordx4 v[156:159], v[150:151], off offset:192
	global_load_dwordx4 v[168:171], v[186:187], off offset:128
	global_load_dwordx4 v[152:155], v[186:187], off offset:192
	global_load_dwordx4 v[164:167], v[188:189], off offset:128
	s_nop 0
	global_load_dwordx4 v[148:151], v[188:189], off offset:192
	v_and_b32_e32 v130, 0xffff0000, v130
	v_max_f32_e32 v130, v130, v130
	v_max_f32_e32 v130, 0x21800000, v130
	v_rcp_f32_e32 v209, v130
	v_lshlrev_b32_e32 v130, 16, v131
	v_and_b32_e32 v131, 0xffff0000, v131
	v_max_f32_e32 v130, v130, v130
	v_max_f32_e32 v131, v131, v131
	v_max_f32_e32 v130, 0x21800000, v130
	v_max_f32_e32 v131, 0x21800000, v131
	v_rcp_f32_e32 v130, v130
	v_rcp_f32_e32 v131, v131
	v_pk_mul_f32 v[26:27], v[26:27], v[128:129]
	v_lshlrev_b32_e32 v128, 16, v180
	v_and_b32_e32 v129, 0xffff0000, v180
	v_pk_mul_f32 v[128:129], v[208:209], v[128:129]
	v_lshrrev_b32_e32 v180, 1, v210
	v_pk_mul_f32 v[28:29], v[28:29], v[128:129]
	v_lshlrev_b32_e32 v128, 16, v181
	v_and_b32_e32 v129, 0xffff0000, v181
	v_pk_mul_f32 v[128:129], v[130:131], v[128:129]
	v_and_b32_e32 v131, 31, v210
	v_pk_mul_f32 v[30:31], v[30:31], v[128:129]
	v_ashrrev_i32_e32 v128, 6, v210
	v_lshrrev_b32_e32 v129, 30, v128
	v_add_u32_e32 v129, v128, v129
	v_and_b32_e32 v130, 0x3ffffc, v129
	v_lshlrev_b32_e32 v129, 5, v129
	v_sub_u32_e32 v128, v128, v130
	v_mul_lo_u32 v130, v182, s31
	v_and_or_b32 v129, v129, s33, v131
	v_mul_lo_u32 v129, v129, s31
	v_and_b32_e32 v180, 16, v180
	v_add3_u32 v209, 0, v130, v212
	v_lshl_or_b32 v128, v128, 6, v131
	v_add3_u32 v208, 0, v129, v180
	s_waitcnt vmcnt(15)
	ds_write_b128 v209, v[132:135] offset:2048
	s_waitcnt vmcnt(14)
	ds_write_b128 v209, v[136:139] offset:12288
	s_waitcnt vmcnt(13)
	ds_write_b128 v209, v[140:143] offset:22528
	s_waitcnt vmcnt(12)
	ds_write_b128 v209, v[144:147] offset:32768
	s_waitcnt vmcnt(11)
	ds_write_b128 v209, v[192:195] offset:43008
	s_waitcnt vmcnt(10)
	ds_write_b128 v209, v[196:199] offset:53248
	s_waitcnt vmcnt(9)
	ds_write_b128 v209, v[200:203] offset:63488
	v_add_u32_e32 v193, 0x12000, v209
	v_mul_lo_u32 v128, v128, s31
	s_waitcnt vmcnt(8)
	ds_write_b128 v193, v[204:207]
	s_waitcnt lgkmcnt(0)
	s_barrier
; #define F_LOAD(fa, fb, so_, ks_) { _Pragma("unroll") for (int it = 0; it < WI; ++it) fa[it] = *(const bf16x8*)(rP + (so_) + it * 32 * LROW + (ks_) * 32); \
;                                   _Pragma("unroll") for (int jt = 0; jt < 2; ++jt) fb[jt] = *(const bf16x8*)(rQ + (so_) + jt * 32 * LROW + (ks_) * 32); }
; #define F_LOAD(fa, fb, so_, ks_) { _Pragma("unroll") for (int it = 0; it < WI; ++it) fa[it] = *(const bf16x8*)(rP + (so_) + it * 32 * LROW + (ks_) * 32); \
;                                   _Pragma("unroll") for (int jt = 0; jt < 2; ++jt) fb[jt] = *(const bf16x8*)(rQ + (so_) + jt * 32 * LROW + (ks_) * 32); }
; #define G_HALF(pl, ql, ps, qs, kt_) { const int k4_ = min((kt_) + 4, nk - 1); \
;         SB G_LOAD(pl, ql, k4_) F_LOAD(fa1, fb1, cur, 1) SB G_MFMA(fa0, fb0) SB G_STORE(ps, qs, wr) F_LOAD(fa0, fb0, nxt, 0) SB G_MFMA(fa1, fb1) SB \
;         __syncthreads(); { const int t_ = cur; cur = nxt; nxt = wr; wr = t_; } }
; #define F_LOAD(fa, fb, so_, ks_) { _Pragma("unroll") for (int it = 0; it < WI; ++it) fa[it] = *(const bf16x8*)(rP + (so_) + it * 32 * LROW + (ks_) * 32); \
;                                   _Pragma("unroll") for (int jt = 0; jt < 2; ++jt) fb[jt] = *(const bf16x8*)(rQ + (so_) + jt * 32 * LROW + (ks_) * 32); }
; #define G_HALF(pl, ql, ps, qs, kt_) { const int k4_ = min((kt_) + 4, nk - 1); \
;         SB R_BURST1(fb0, fb1, cur, 1, pl, ql, k4_, ps, qs, wr) R_BURST2(fb1, fb0, nxt, 0, ps, qs, wr) \
;         __syncthreads(); { const int t_ = cur; cur = nxt; nxt = wr; wr = t_; } }
; #define F_LOAD(fa, fb, so_, ks_) { _Pragma("unroll") for (int it = 0; it < WI; ++it) fa[it] = *(const bf16x8*)(rP + (so_) + it * 32 * LROW + (ks_) * 32); \
;                                   _Pragma("unroll") for (int jt = 0; jt < 2; ++jt) fb[jt] = *(const bf16x8*)(rQ + (so_) + jt * 32 * LROW + (ks_) * 32); }
;     ...
;     __syncthreads();
;     F_LOAD(fa0, fb0, 0, 0)
;     int cur = 0, nxt = STAGE, wr = 2 * STAGE;
;     int kt = 0;
; #pragma unroll 1
;     for (; kt + 3 <= nk; kt += 3) {
;         G_HALF(p1, q1, p2, q2, kt)
;         G_HALF(p2, q2, p0, q0, kt + 1)
;         G_HALF(p0, q0, p1, q1, kt + 2)
;     }
	ds_read_b128 v[144:147], v208 offset:2048
	ds_read_b128 v[140:143], v208 offset:4608
	ds_read_b128 v[136:139], v208 offset:7168
	ds_read_b128 v[132:135], v208 offset:9728
	v_add3_u32 v211, 0, v128, v180
	ds_read_b128 v[180:183], v211 offset:22528
	ds_read_b128 v[128:131], v211 offset:25088
	s_add_u32 s18, s56, s54
	s_addc_u32 s19, s57, 0
	s_add_u32 s12, s56, s12
	s_addc_u32 s13, s57, s13
	v_add_u32_e32 v210, 0x5800, v211
	v_add_u32_e32 v192, 0x19800, v209
	v_add_u32_e32 v195, 0x14800, v209
	v_add_u32_e32 v197, 0x14800, v208
	v_add_u32_e32 v198, 0x19800, v211
	v_add_u32_e32 v194, 0x17000, v209
	v_add_u32_e32 v196, 0x1c000, v209
	v_add_u32_e32 v199, 0x1a200, v211
	v_add_u32_e32 v200, 0x15200, v208
	v_add_u32_e32 v201, 0x15c00, v208
	v_add_u32_e32 v202, 0x16600, v208
	v_add_u32_e32 v203, 0x19820, v211
	v_add_u32_e32 v204, 0x14820, v208
	v_add_u32_e32 v205, 0x1a220, v211
	v_add_u32_e32 v206, 0x15220, v208
	v_add_u32_e32 v207, 0x15c20, v208
	v_add_u32_e32 v214, 0x16620, v208
	v_lshl_add_u64 v[188:189], s[18:19], 0, v[190:191]
	v_lshl_add_u64 v[190:191], s[12:13], 0, v[190:191]
	s_waitcnt lgkmcnt(0)
.LBB0_995:
	s_waitcnt lgkmcnt(4)
	v_mfma_f32_32x32x16_bf16 v[112:127], v[144:147], v[180:183], v[112:127]
	ds_read_b128 v[216:219], v211 offset:22560
	s_waitcnt vmcnt(7)
	ds_write_b128 v195, v[176:179]
	s_waitcnt lgkmcnt(5)
	v_mfma_f32_32x32x16_bf16 v[0:15], v[144:147], v[128:131], v[0:15]
	ds_read_b128 v[176:179], v208 offset:2080
	global_load_dwordx4 v[144:147], v250, s[98:99] offset:256
	s_waitcnt lgkmcnt(5)
	v_mfma_f32_32x32x16_bf16 v[96:111], v[140:143], v[180:183], v[96:111]
	ds_read_b128 v[222:225], v211 offset:25120
	s_waitcnt vmcnt(6)
	ds_write_b128 v194, v[172:175]
	v_mfma_f32_32x32x16_bf16 v[32:47], v[140:143], v[128:131], v[32:47]
	ds_read_b128 v[172:175], v208 offset:4640
	global_load_dwordx4 v[140:143], v251, s[98:99] offset:256
	s_waitcnt lgkmcnt(7)
	v_mfma_f32_32x32x16_bf16 v[80:95], v[136:139], v[180:183], v[80:95]
	s_waitcnt vmcnt(5)
	ds_write_b128 v192, v[168:171]
	v_mfma_f32_32x32x16_bf16 v[48:63], v[136:139], v[128:131], v[48:63]
	ds_read_b128 v[168:171], v208 offset:7200
	global_load_dwordx4 v[136:139], v250, s[100:101] offset:256
	s_waitcnt lgkmcnt(8)
	v_mfma_f32_32x32x16_bf16 v[64:79], v[132:135], v[180:183], v[64:79]
	s_waitcnt vmcnt(4)
	ds_write_b128 v196, v[164:167]
	v_mfma_f32_32x32x16_bf16 v[16:31], v[132:135], v[128:131], v[16:31]
	ds_read_b128 v[132:135], v208 offset:9760
	global_load_dwordx4 v[128:131], v251, s[100:101] offset:256
	s_waitcnt lgkmcnt(7)
	v_mfma_f32_32x32x16_bf16 v[112:127], v[176:179], v[216:219], v[112:127]
	ds_read_b128 v[164:167], v211 offset:63488
	s_waitcnt lgkmcnt(7)
	v_mfma_f32_32x32x16_bf16 v[0:15], v[176:179], v[222:225], v[0:15]
	ds_read_b128 v[176:179], v208 offset:43008
	s_waitcnt lgkmcnt(6)
	v_mfma_f32_32x32x16_bf16 v[96:111], v[172:175], v[216:219], v[96:111]
	ds_read_b128 v[180:183], v210 offset:43520
	v_mfma_f32_32x32x16_bf16 v[32:47], v[172:175], v[222:225], v[32:47]
	ds_read_b128 v[172:175], v208 offset:45568
	s_waitcnt lgkmcnt(6)
	v_mfma_f32_32x32x16_bf16 v[80:95], v[168:171], v[216:219], v[80:95]
	v_mfma_f32_32x32x16_bf16 v[48:63], v[168:171], v[222:225], v[48:63]
	ds_read_b128 v[168:171], v208 offset:48128
	s_waitcnt lgkmcnt(5)
	v_mfma_f32_32x32x16_bf16 v[64:79], v[132:135], v[216:219], v[64:79]
	v_mfma_f32_32x32x16_bf16 v[16:31], v[132:135], v[222:225], v[16:31]
	ds_read_b128 v[132:135], v208 offset:50688
	s_barrier
	s_min_u32 s6, s11, 26
	s_waitcnt lgkmcnt(4)
	v_mfma_f32_32x32x16_bf16 v[112:127], v[176:179], v[164:167], v[112:127]
	ds_read_b128 v[216:219], v211 offset:63520
	ds_write_b128 v209, v[160:163] offset:2048
	s_waitcnt lgkmcnt(5)
	v_mfma_f32_32x32x16_bf16 v[0:15], v[176:179], v[180:183], v[0:15]
	global_load_dwordx4 v[176:179], v250, s[98:99] offset:320
	ds_read_b128 v[160:163], v208 offset:43040
	s_waitcnt lgkmcnt(5)
	v_mfma_f32_32x32x16_bf16 v[96:111], v[172:175], v[164:167], v[96:111]
	ds_read_b128 v[222:225], v210 offset:43552
	ds_write_b128 v209, v[156:159] offset:12288
	v_mfma_f32_32x32x16_bf16 v[32:47], v[172:175], v[180:183], v[32:47]
	global_load_dwordx4 v[172:175], v251, s[98:99] offset:320
	ds_read_b128 v[156:159], v208 offset:45600
	s_waitcnt lgkmcnt(7)
	v_mfma_f32_32x32x16_bf16 v[80:95], v[168:171], v[164:167], v[80:95]
	ds_write_b128 v209, v[152:155] offset:22528
	v_mfma_f32_32x32x16_bf16 v[48:63], v[168:171], v[180:183], v[48:63]
	global_load_dwordx4 v[168:171], v250, s[100:101] offset:320
	ds_read_b128 v[152:155], v208 offset:48160
	s_waitcnt lgkmcnt(8)
	v_mfma_f32_32x32x16_bf16 v[64:79], v[132:135], v[164:167], v[64:79]
	s_waitcnt vmcnt(7)
	ds_write_b128 v209, v[148:151] offset:32768
	v_mfma_f32_32x32x16_bf16 v[16:31], v[132:135], v[180:183], v[16:31]
	global_load_dwordx4 v[164:167], v251, s[100:101] offset:320
	ds_read_b128 v[132:135], v208 offset:50720
	s_waitcnt lgkmcnt(7)
	v_mfma_f32_32x32x16_bf16 v[112:127], v[160:163], v[216:219], v[112:127]
	ds_read_b128 v[148:151], v198
	s_waitcnt lgkmcnt(7)
	v_mfma_f32_32x32x16_bf16 v[0:15], v[160:163], v[222:225], v[0:15]
	ds_read_b128 v[160:163], v197
	s_waitcnt lgkmcnt(6)
	v_mfma_f32_32x32x16_bf16 v[96:111], v[156:159], v[216:219], v[96:111]
	ds_read_b128 v[180:183], v199
	v_mfma_f32_32x32x16_bf16 v[32:47], v[156:159], v[222:225], v[32:47]
	ds_read_b128 v[156:159], v200
	s_waitcnt lgkmcnt(6)
	v_mfma_f32_32x32x16_bf16 v[80:95], v[152:155], v[216:219], v[80:95]
	v_mfma_f32_32x32x16_bf16 v[48:63], v[152:155], v[222:225], v[48:63]
	ds_read_b128 v[152:155], v201
	s_waitcnt lgkmcnt(5)
	v_mfma_f32_32x32x16_bf16 v[64:79], v[132:135], v[216:219], v[64:79]
	v_mfma_f32_32x32x16_bf16 v[16:31], v[132:135], v[222:225], v[16:31]
	ds_read_b128 v[132:135], v202
	s_barrier
; #define G_HALF(pl, ql, ps, qs, kt_) { const int k4_ = min((kt_) + 4, nk - 1); \
;         SB G_LOAD(pl, ql, k4_) F_LOAD(fa1, fb1, cur, 1) SB G_MFMA(fa0, fb0) SB G_STORE(ps, qs, wr) F_LOAD(fa0, fb0, nxt, 0) SB G_MFMA(fa1, fb1) SB \
;         __syncthreads(); { const int t_ = cur; cur = nxt; nxt = wr; wr = t_; } }
; #define G_HALF(pl, ql, ps, qs, kt_) { const int k4_ = min((kt_) + 4, nk - 1); \
;         SB R_BURST1(fb0, fb1, cur, 1, pl, ql, k4_, ps, qs, wr) R_BURST2(fb1, fb0, nxt, 0, ps, qs, wr) \
;         __syncthreads(); { const int t_ = cur; cur = nxt; nxt = wr; wr = t_; } }
; #define G_HALF(pl, ql, ps, qs, kt_) { const int k4_ = min((kt_) + 4, nk - 1); \
;         SB R_BURST1(fb0, fb1, cur, 1, pl, ql, k4_, ps, qs, wr) R_BURST2(fb1, fb0, nxt, 0, ps, qs, wr) \
;         __syncthreads(); { const int t_ = cur; cur = nxt; nxt = wr; wr = t_; } }
;     ...
; #pragma unroll 1
;     for (; kt + 3 <= nk; kt += 3) {
;         G_HALF(p1, q1, p2, q2, kt)
;         G_HALF(p2, q2, p0, q0, kt + 1)
;         G_HALF(p0, q0, p1, q1, kt + 2)
;     }
;     if (kt < nk) G_HALF(p1, q1, p2, q2, kt)
;     if (kt + 1 < nk) G_HALF(p2, q2, p0, q0, kt + 1)
	s_min_u32 s6, s11, 25
	s_waitcnt lgkmcnt(4)
	v_mfma_f32_32x32x16_bf16 v[112:127], v[160:163], v[148:151], v[112:127]
	ds_read_b128 v[216:219], v203
	s_waitcnt vmcnt(7)
	ds_write_b128 v209, v[144:147] offset:43008
	s_waitcnt lgkmcnt(5)
	v_mfma_f32_32x32x16_bf16 v[0:15], v[160:163], v[180:183], v[0:15]
	global_load_dwordx4 v[160:163], v250, s[98:99] offset:384
	ds_read_b128 v[144:147], v204
	s_waitcnt lgkmcnt(5)
	v_mfma_f32_32x32x16_bf16 v[96:111], v[156:159], v[148:151], v[96:111]
	ds_read_b128 v[222:225], v205
	s_waitcnt vmcnt(7)
	ds_write_b128 v209, v[140:143] offset:53248
	v_mfma_f32_32x32x16_bf16 v[32:47], v[156:159], v[180:183], v[32:47]
	global_load_dwordx4 v[156:159], v251, s[98:99] offset:384
	ds_read_b128 v[140:143], v206
	s_waitcnt lgkmcnt(7)
	v_mfma_f32_32x32x16_bf16 v[80:95], v[152:155], v[148:151], v[80:95]
	s_waitcnt vmcnt(7)
	ds_write_b128 v209, v[136:139] offset:63488
	v_mfma_f32_32x32x16_bf16 v[48:63], v[152:155], v[180:183], v[48:63]
	global_load_dwordx4 v[152:155], v250, s[100:101] offset:384
	ds_read_b128 v[136:139], v207
	s_waitcnt lgkmcnt(8)
	v_mfma_f32_32x32x16_bf16 v[64:79], v[132:135], v[148:151], v[64:79]
	s_waitcnt vmcnt(7)
	ds_write_b128 v193, v[128:131]
	v_mfma_f32_32x32x16_bf16 v[16:31], v[132:135], v[180:183], v[16:31]
	ds_read_b128 v[132:135], v214
	global_load_dwordx4 v[148:151], v251, s[100:101] offset:384
	s_waitcnt lgkmcnt(7)
	v_mfma_f32_32x32x16_bf16 v[112:127], v[144:147], v[216:219], v[112:127]
	ds_read_b128 v[180:183], v211 offset:22528
	s_waitcnt lgkmcnt(7)
	v_mfma_f32_32x32x16_bf16 v[0:15], v[144:147], v[222:225], v[0:15]
	ds_read_b128 v[144:147], v208 offset:2048
	s_waitcnt lgkmcnt(6)
	v_mfma_f32_32x32x16_bf16 v[96:111], v[140:143], v[216:219], v[96:111]
	ds_read_b128 v[128:131], v211 offset:25088
	v_mfma_f32_32x32x16_bf16 v[32:47], v[140:143], v[222:225], v[32:47]
	ds_read_b128 v[140:143], v208 offset:4608
	s_waitcnt lgkmcnt(6)
	v_mfma_f32_32x32x16_bf16 v[80:95], v[136:139], v[216:219], v[80:95]
	v_mfma_f32_32x32x16_bf16 v[48:63], v[136:139], v[222:225], v[48:63]
	ds_read_b128 v[136:139], v208 offset:7168
	s_waitcnt lgkmcnt(5)
	v_mfma_f32_32x32x16_bf16 v[64:79], v[132:135], v[216:219], v[64:79]
	v_mfma_f32_32x32x16_bf16 v[16:31], v[132:135], v[222:225], v[16:31]
	ds_read_b128 v[132:135], v208 offset:9728
	s_add_i32 s11, s11, 3
	v_add_u32_e32 v250, 0xc0, v250
	s_cmp_lt_u32 s11, 30
	v_add_u32_e32 v251, 0xc0, v251
	s_barrier
	s_cbranch_scc1 .LBB0_995
	s_waitcnt lgkmcnt(0)
	v_mfma_f32_32x32x16_bf16 v[112:127], v[144:147], v[180:183], v[112:127]
	ds_read_b128 v[214:217], v211 offset:22560
	s_waitcnt vmcnt(7)
	ds_write_b128 v195, v[176:179]
	ds_read_b128 v[200:203], v208 offset:2080
	v_mfma_f32_32x32x16_bf16 v[96:111], v[140:143], v[180:183], v[96:111]
	ds_read_b128 v[188:191], v211 offset:25120
	s_waitcnt vmcnt(6)
	ds_write_b128 v194, v[172:175]
	ds_read_b128 v[204:207], v208 offset:4640
	v_mfma_f32_32x32x16_bf16 v[80:95], v[136:139], v[180:183], v[80:95]
	s_waitcnt vmcnt(5)
	ds_write_b128 v192, v[168:171]
	ds_read_b128 v[192:195], v208 offset:7200
	v_mfma_f32_32x32x16_bf16 v[64:79], v[132:135], v[180:183], v[64:79]
	s_waitcnt vmcnt(4)
	ds_write_b128 v196, v[164:167]
	ds_read_b128 v[196:199], v208 offset:9760
	s_waitcnt lgkmcnt(7)
	v_mfma_f32_32x32x16_bf16 v[112:127], v[200:203], v[214:217], v[112:127]
	ds_read_b128 v[222:225], v211 offset:63488
	ds_read_b128 v[184:187], v208 offset:43008
	s_waitcnt lgkmcnt(6)
	v_mfma_f32_32x32x16_bf16 v[96:111], v[204:207], v[214:217], v[96:111]
	ds_read_b128 v[164:167], v210 offset:43520
	ds_read_b128 v[176:179], v208 offset:45568
	s_waitcnt lgkmcnt(6)
	v_mfma_f32_32x32x16_bf16 v[80:95], v[192:195], v[214:217], v[80:95]
	ds_read_b128 v[172:175], v208 offset:48128
	s_waitcnt lgkmcnt(5)
	v_mfma_f32_32x32x16_bf16 v[64:79], v[196:199], v[214:217], v[64:79]
	ds_read_b128 v[168:171], v208 offset:50688
	s_waitcnt lgkmcnt(0)
	s_barrier
	v_mfma_f32_32x32x16_bf16 v[112:127], v[184:187], v[222:225], v[112:127]
	ds_read_b128 v[214:217], v211 offset:63520
	s_waitcnt vmcnt(3)
	ds_write_b128 v209, v[160:163] offset:2048
	ds_read_b128 v[180:183], v208 offset:43040
	v_mfma_f32_32x32x16_bf16 v[96:111], v[176:179], v[222:225], v[96:111]
	ds_read_b128 v[160:163], v210 offset:43552
	s_waitcnt vmcnt(2)
	ds_write_b128 v209, v[156:159] offset:12288
	ds_read_b128 v[156:159], v208 offset:45600
	v_mfma_f32_32x32x16_bf16 v[80:95], v[172:175], v[222:225], v[80:95]
	s_waitcnt vmcnt(1)
	ds_write_b128 v209, v[152:155] offset:22528
	ds_read_b128 v[152:155], v208 offset:48160
	v_mfma_f32_32x32x16_bf16 v[64:79], v[168:171], v[222:225], v[64:79]
	s_waitcnt vmcnt(0)
	ds_write_b128 v209, v[148:151] offset:32768
	ds_read_b128 v[148:151], v208 offset:50720
	s_waitcnt lgkmcnt(7)
	v_mfma_f32_32x32x16_bf16 v[112:127], v[180:183], v[214:217], v[112:127]
	s_waitcnt lgkmcnt(4)
	v_mfma_f32_32x32x16_bf16 v[96:111], v[156:159], v[214:217], v[96:111]
	s_waitcnt lgkmcnt(2)
	v_mfma_f32_32x32x16_bf16 v[80:95], v[152:155], v[214:217], v[80:95]
	s_waitcnt lgkmcnt(0)
	v_mfma_f32_32x32x16_bf16 v[64:79], v[148:151], v[214:217], v[64:79]
	s_add_i32 s12, s14, 0x100
	v_mov_b32_e32 v221, v220
	s_ashr_i32 s13, s12, 31
	s_barrier
; DI u32x2 pk4(float a, float b, float c, float d) { u32x2 r; r.x = pk2(a, b); r.y = pk2(c, d); return r; }
; DI float bf_lo(unsigned u) { return __uint_as_float(u << 16); }
; DI float bf_hi(unsigned u) { return __uint_as_float(u & 0xffff0000u); }
; template <int WI, int WGJ, class GetF, class FinF>
; DI void staged_rows(unsigned char* lds, int tid, GetF get, FinF fin) {
;     ...
;     for (int jt = 0; jt < 2; ++jt) {
;         unsigned char* wrow = lds + (wj * 32 + ln) * RS + (wi * WI * 32 + 4 * h) * 2;
; #pragma unroll
;         for (int it = 0; it < WI; ++it)
; #pragma unroll
;             for (int g = 0; g < 4; ++g) *(u32x2*)(wrow + (it * 32 + 8 * g) * 2) = get(it, jt, g);
;         __syncthreads();
; DI void phase4(const Params& p, unsigned char* smem, int tid) {
;     ...
;             int te = tid; asm volatile("" : "+v"(te));
;             const unsigned char* gb = ws + OFF_G + ((size_t)((4 + f) * 64 + tt) * 8 + (te >> 6)) * 16384 + (te & 63) * 16;
;             staged_rows<4, 4>(lds, te,
;                 [&](int it, int jt, int g) { const u32x4 b4 = *(const u32x4*)(gb + ((it * 2 + jt) * 2 + (g >> 1)) * 1024); const int e0 = (g & 1) * 2;
;                     const float g0 = fmaxf(bf_lo(b4[e0]), 8.6736174e-19f), g1 = fmaxf(bf_hi(b4[e0]), 8.6736174e-19f);
;                     const float g2 = fmaxf(bf_lo(b4[e0 + 1]), 8.6736174e-19f), g3 = fmaxf(bf_hi(b4[e0 + 1]), 8.6736174e-19f);
;                     return pk4(acc[it][jt][4 * g] * g0, acc[it][jt][4 * g + 1] * g1, acc[it][jt][4 * g + 2] * g2, acc[it][jt][4 * g + 3] * g3); },
	s_lshl_b64 s[12:13], s[12:13], 17
	v_ashrrev_i32_e32 v208, 6, v221
	v_ashrrev_i32_e32 v209, 31, v208
	s_add_u32 s12, s24, s12
	v_lshlrev_b64 v[210:211], 14, v[208:209]
	s_addc_u32 s13, s25, s13
	v_lshlrev_b32_e32 v209, 4, v221
	v_lshl_add_u64 v[210:211], s[12:13], 0, v[210:211]
	v_and_b32_e32 v212, 0x3f0, v209
	v_lshl_add_u64 v[216:217], v[210:211], 0, v[212:213]
	global_load_dwordx4 v[222:225], v[216:217], off nt
	global_load_dwordx4 v[226:229], v[216:217], off offset:1024 nt
	v_add_co_u32_e32 v214, vcc, s42, v216
	v_lshrrev_b32_e32 v210, 2, v221
	s_nop 0
	v_addc_co_u32_e32 v215, vcc, 0, v217, vcc
	global_load_dwordx4 v[230:233], v[214:215], off offset:-4096 nt
	v_lshrrev_b32_e32 v211, 30, v208
	v_and_b32_e32 v212, 8, v210
	v_add_u32_e32 v210, v208, v211
	v_and_b32_e32 v211, 0x7ffffc, v210
	v_and_b32_e32 v209, 31, v221
	v_sub_u32_e32 v208, v208, v211
	v_lshlrev_b32_e32 v210, 6, v210
	v_lshl_or_b32 v208, v208, 5, v209
	v_add_co_u32_e32 v218, vcc, s40, v216
	v_and_b32_e32 v234, 0xffffff00, v210
	s_nop 0
	v_addc_co_u32_e32 v219, vcc, 0, v217, vcc
	v_mul_lo_u32 v235, v208, s50
	global_load_dwordx4 v[208:211], v[218:219], off offset:1024 nt
	v_add3_u32 v234, 0, v235, v234
	v_add_u32_e32 v212, v234, v212
	v_add_u32_e32 v212, 0x800, v212
	s_lshl_b32 s11, s53, 9
	s_add_u32 s12, s3, s11
	s_mov_b32 s6, 0
	s_addc_u32 s13, s16, 0
	s_waitcnt vmcnt(3)
	v_lshlrev_b32_e32 v234, 16, v222
	v_and_b32_e32 v222, 0xffff0000, v222
	v_lshlrev_b32_e32 v235, 16, v223
	v_and_b32_e32 v223, 0xffff0000, v223
	v_lshlrev_b32_e32 v236, 16, v224
	v_and_b32_e32 v224, 0xffff0000, v224
	v_lshlrev_b32_e32 v237, 16, v225
	v_and_b32_e32 v225, 0xffff0000, v225
	s_waitcnt vmcnt(2)
	v_lshlrev_b32_e32 v238, 16, v226
	v_and_b32_e32 v226, 0xffff0000, v226
	v_lshlrev_b32_e32 v239, 16, v227
	v_and_b32_e32 v227, 0xffff0000, v227
	v_max_f32_e32 v234, v234, v234
	v_max_f32_e32 v241, v222, v222
	v_max_f32_e32 v235, v235, v235
	v_max_f32_e32 v242, v223, v223
	v_max_f32_e32 v236, v236, v236
	v_max_f32_e32 v243, v224, v224
	v_max_f32_e32 v237, v237, v237
	v_max_f32_e32 v244, v225, v225
	v_max_f32_e32 v245, v226, v226
	v_max_f32_e32 v246, v227, v227
	v_max_f32_e32 v222, 0x21800000, v234
	v_max_f32_e32 v223, 0x21800000, v241
	v_max_f32_e32 v224, 0x21800000, v235
	v_max_f32_e32 v225, 0x21800000, v242
	v_max_f32_e32 v226, 0x21800000, v236
	v_max_f32_e32 v227, 0x21800000, v243
	v_max_f32_e32 v234, 0x21800000, v237
	v_max_f32_e32 v235, 0x21800000, v244
	v_pk_mul_f32 v[112:113], v[112:113], v[222:223]
	v_pk_mul_f32 v[114:115], v[114:115], v[224:225]
	v_pk_mul_f32 v[116:117], v[116:117], v[226:227]
	v_pk_mul_f32 v[118:119], v[118:119], v[234:235]
	v_lshlrev_b32_e32 v240, 16, v228
	v_cvt_pk_bf16_f32 v112, v112, v113
	v_cvt_pk_bf16_f32 v113, v114, v115
	v_cvt_pk_bf16_f32 v114, v116, v117
	v_cvt_pk_bf16_f32 v115, v118, v119
	ds_write2_b64 v212, v[112:113], v[114:115] offset1:2
	v_max_f32_e32 v112, v240, v240
	v_max_f32_e32 v118, 0x21800000, v112
	v_and_b32_e32 v112, 0xffff0000, v228
	v_max_f32_e32 v238, v238, v238
	v_max_f32_e32 v112, v112, v112
	v_max_f32_e32 v236, 0x21800000, v238
	v_max_f32_e32 v237, 0x21800000, v245
	v_max_f32_e32 v119, 0x21800000, v112
	v_lshlrev_b32_e32 v112, 16, v229
	v_pk_mul_f32 v[120:121], v[120:121], v[236:237]
	v_max_f32_e32 v112, v112, v112
	v_cvt_pk_bf16_f32 v116, v120, v121
	v_max_f32_e32 v120, 0x21800000, v112
	v_and_b32_e32 v112, 0xffff0000, v229
	v_max_f32_e32 v121, v112, v112
	global_load_dwordx4 v[112:115], v[214:215], off nt
	v_max_f32_e32 v239, v239, v239
	v_max_f32_e32 v238, 0x21800000, v239
	v_max_f32_e32 v239, 0x21800000, v246
	v_max_f32_e32 v121, 0x21800000, v121
	v_pk_mul_f32 v[122:123], v[122:123], v[238:239]
	v_pk_mul_f32 v[118:119], v[124:125], v[118:119]
	v_pk_mul_f32 v[120:121], v[126:127], v[120:121]
	v_cvt_pk_bf16_f32 v117, v122, v123
	v_cvt_pk_bf16_f32 v118, v118, v119
	v_cvt_pk_bf16_f32 v119, v120, v121
	ds_write2_b64 v212, v[116:117], v[118:119] offset0:4 offset1:6
	s_waitcnt vmcnt(2)
	v_lshlrev_b32_e32 v116, 16, v230
	v_and_b32_e32 v117, 0xffff0000, v230
	v_lshlrev_b32_e32 v118, 16, v231
	v_and_b32_e32 v119, 0xffff0000, v231
	v_max_f32_e32 v116, v116, v116
	v_max_f32_e32 v117, v117, v117
	v_max_f32_e32 v118, v118, v118
	v_max_f32_e32 v119, v119, v119
	v_max_f32_e32 v116, 0x21800000, v116
	v_max_f32_e32 v117, 0x21800000, v117
	v_max_f32_e32 v118, 0x21800000, v118
	v_max_f32_e32 v119, 0x21800000, v119
	v_pk_mul_f32 v[96:97], v[96:97], v[116:117]
	v_pk_mul_f32 v[98:99], v[98:99], v[118:119]
	v_cvt_pk_bf16_f32 v96, v96, v97
	v_cvt_pk_bf16_f32 v97, v98, v99
	v_lshlrev_b32_e32 v98, 16, v232
	v_and_b32_e32 v99, 0xffff0000, v232
	v_lshlrev_b32_e32 v116, 16, v233
	v_and_b32_e32 v121, 0xffff0000, v233
	v_max_f32_e32 v98, v98, v98
	v_max_f32_e32 v99, v99, v99
	v_max_f32_e32 v116, v116, v116
	v_max_f32_e32 v121, v121, v121
	v_max_f32_e32 v98, 0x21800000, v98
	v_max_f32_e32 v99, 0x21800000, v99
	v_max_f32_e32 v120, 0x21800000, v116
	v_max_f32_e32 v121, 0x21800000, v121
	v_pk_mul_f32 v[98:99], v[100:101], v[98:99]
	v_pk_mul_f32 v[100:101], v[102:103], v[120:121]
	v_cvt_pk_bf16_f32 v98, v98, v99
	v_cvt_pk_bf16_f32 v99, v100, v101
	global_load_dwordx4 v[116:119], v[214:215], off offset:1024 nt
	ds_write2_b64 v212, v[96:97], v[98:99] offset0:8 offset1:10
	s_waitcnt vmcnt(2)
; DI u32x2 pk4(float a, float b, float c, float d) { u32x2 r; r.x = pk2(a, b); r.y = pk2(c, d); return r; }
; DI float bf_lo(unsigned u) { return __uint_as_float(u << 16); }
; DI float bf_hi(unsigned u) { return __uint_as_float(u & 0xffff0000u); }
; template <int WI, int WGJ, class GetF, class FinF>
; DI void staged_rows(unsigned char* lds, int tid, GetF get, FinF fin) {
;     ...
;     for (int jt = 0; jt < 2; ++jt) {
;         unsigned char* wrow = lds + (wj * 32 + ln) * RS + (wi * WI * 32 + 4 * h) * 2;
; #pragma unroll
;         for (int it = 0; it < WI; ++it)
; #pragma unroll
;             for (int g = 0; g < 4; ++g) *(u32x2*)(wrow + (it * 32 + 8 * g) * 2) = get(it, jt, g);
;         __syncthreads();
; DI void phase4(const Params& p, unsigned char* smem, int tid) {
;     ...
;                 [&](int it, int jt, int g) { const u32x4 b4 = *(const u32x4*)(gb + ((it * 2 + jt) * 2 + (g >> 1)) * 1024); const int e0 = (g & 1) * 2;
;                     const float g0 = fmaxf(bf_lo(b4[e0]), 8.6736174e-19f), g1 = fmaxf(bf_hi(b4[e0]), 8.6736174e-19f);
;                     const float g2 = fmaxf(bf_lo(b4[e0 + 1]), 8.6736174e-19f), g3 = fmaxf(bf_hi(b4[e0 + 1]), 8.6736174e-19f);
;                     return pk4(acc[it][jt][4 * g] * g0, acc[it][jt][4 * g + 1] * g1, acc[it][jt][4 * g + 2] * g2, acc[it][jt][4 * g + 3] * g3); },
	v_lshlrev_b32_e32 v96, 16, v208
	v_and_b32_e32 v97, 0xffff0000, v208
	v_max_f32_e32 v96, v96, v96
	v_max_f32_e32 v97, v97, v97
	v_max_f32_e32 v96, 0x21800000, v96
	v_max_f32_e32 v97, 0x21800000, v97
	v_pk_mul_f32 v[96:97], v[104:105], v[96:97]
	v_lshlrev_b32_e32 v98, 16, v209
	v_and_b32_e32 v99, 0xffff0000, v209
	v_cvt_pk_bf16_f32 v102, v96, v97
	v_lshlrev_b32_e32 v96, 16, v210
	v_max_f32_e32 v98, v98, v98
	v_max_f32_e32 v99, v99, v99
	v_max_f32_e32 v96, v96, v96
	v_max_f32_e32 v98, 0x21800000, v98
	v_max_f32_e32 v99, 0x21800000, v99
	v_max_f32_e32 v104, 0x21800000, v96
	v_and_b32_e32 v96, 0xffff0000, v210
	v_pk_mul_f32 v[98:99], v[106:107], v[98:99]
	v_max_f32_e32 v105, v96, v96
	v_add_co_u32_e32 v96, vcc, s44, v216
	v_lshlrev_b32_e32 v106, 16, v211
	v_and_b32_e32 v107, 0xffff0000, v211
	v_addc_co_u32_e32 v97, vcc, 0, v217, vcc
	v_max_f32_e32 v106, v106, v106
	v_max_f32_e32 v107, v107, v107
	v_cvt_pk_bf16_f32 v103, v98, v99
	global_load_dwordx4 v[98:101], v[96:97], off nt
	v_max_f32_e32 v105, 0x21800000, v105
	v_max_f32_e32 v106, 0x21800000, v106
	v_max_f32_e32 v107, 0x21800000, v107
	v_pk_mul_f32 v[104:105], v[108:109], v[104:105]
	v_pk_mul_f32 v[106:107], v[110:111], v[106:107]
	v_cvt_pk_bf16_f32 v104, v104, v105
	v_cvt_pk_bf16_f32 v105, v106, v107
	ds_write2_b64 v212, v[102:103], v[104:105] offset0:12 offset1:14
	s_waitcnt vmcnt(2)
	v_lshlrev_b32_e32 v102, 16, v112
	v_and_b32_e32 v103, 0xffff0000, v112
	v_max_f32_e32 v102, v102, v102
	v_max_f32_e32 v103, v103, v103
	v_max_f32_e32 v102, 0x21800000, v102
	v_max_f32_e32 v103, 0x21800000, v103
	v_lshlrev_b32_e32 v104, 16, v113
	v_and_b32_e32 v105, 0xffff0000, v113
	v_max_f32_e32 v104, v104, v104
	v_max_f32_e32 v105, v105, v105
	v_pk_mul_f32 v[80:81], v[80:81], v[102:103]
	v_max_f32_e32 v104, 0x21800000, v104
	v_max_f32_e32 v105, 0x21800000, v105
	v_cvt_pk_bf16_f32 v102, v80, v81
	v_lshlrev_b32_e32 v80, 16, v114
	v_pk_mul_f32 v[82:83], v[82:83], v[104:105]
	v_max_f32_e32 v80, v80, v80
	v_cvt_pk_bf16_f32 v103, v82, v83
	v_max_f32_e32 v104, 0x21800000, v80
	global_load_dwordx4 v[80:83], v[96:97], off offset:1024 nt
	v_and_b32_e32 v105, 0xffff0000, v114
	v_lshlrev_b32_e32 v106, 16, v115
	v_and_b32_e32 v107, 0xffff0000, v115
	v_max_f32_e32 v105, v105, v105
	v_max_f32_e32 v106, v106, v106
	v_max_f32_e32 v107, v107, v107
	v_max_f32_e32 v105, 0x21800000, v105
	v_max_f32_e32 v106, 0x21800000, v106
	v_max_f32_e32 v107, 0x21800000, v107
	v_pk_mul_f32 v[84:85], v[84:85], v[104:105]
	v_pk_mul_f32 v[86:87], v[86:87], v[106:107]
	v_cvt_pk_bf16_f32 v84, v84, v85
	v_cvt_pk_bf16_f32 v85, v86, v87
	ds_write2_b64 v212, v[102:103], v[84:85] offset0:16 offset1:18
	s_waitcnt vmcnt(2)
	v_lshlrev_b32_e32 v84, 16, v116
	v_and_b32_e32 v85, 0xffff0000, v116
	v_lshlrev_b32_e32 v86, 16, v117
	v_and_b32_e32 v87, 0xffff0000, v117
	v_max_f32_e32 v84, v84, v84
	v_max_f32_e32 v85, v85, v85
	v_max_f32_e32 v86, v86, v86
	v_max_f32_e32 v87, v87, v87
	v_max_f32_e32 v84, 0x21800000, v84
	v_max_f32_e32 v85, 0x21800000, v85
	v_max_f32_e32 v86, 0x21800000, v86
	v_max_f32_e32 v87, 0x21800000, v87
	v_pk_mul_f32 v[84:85], v[88:89], v[84:85]
	v_pk_mul_f32 v[86:87], v[90:91], v[86:87]
	v_cvt_pk_bf16_f32 v84, v84, v85
	v_cvt_pk_bf16_f32 v85, v86, v87
	v_lshlrev_b32_e32 v86, 16, v118
	v_and_b32_e32 v87, 0xffff0000, v118
	v_lshlrev_b32_e32 v88, 16, v119
	v_and_b32_e32 v89, 0xffff0000, v119
	v_max_f32_e32 v86, v86, v86
	v_max_f32_e32 v87, v87, v87
	v_max_f32_e32 v88, v88, v88
	v_max_f32_e32 v89, v89, v89
	v_max_f32_e32 v86, 0x21800000, v86
	v_max_f32_e32 v87, 0x21800000, v87
	v_max_f32_e32 v88, 0x21800000, v88
	v_max_f32_e32 v89, 0x21800000, v89
	v_pk_mul_f32 v[86:87], v[92:93], v[86:87]
	v_pk_mul_f32 v[88:89], v[94:95], v[88:89]
	v_cvt_pk_bf16_f32 v86, v86, v87
	v_cvt_pk_bf16_f32 v87, v88, v89
	ds_write2_b64 v212, v[84:85], v[86:87] offset0:20 offset1:22
	s_waitcnt vmcnt(1)
	v_lshlrev_b32_e32 v84, 16, v98
	v_and_b32_e32 v85, 0xffff0000, v98
	v_lshlrev_b32_e32 v86, 16, v99
	v_and_b32_e32 v87, 0xffff0000, v99
	v_max_f32_e32 v84, v84, v84
	v_max_f32_e32 v85, v85, v85
	v_max_f32_e32 v86, v86, v86
	v_max_f32_e32 v87, v87, v87
	v_max_f32_e32 v84, 0x21800000, v84
	v_max_f32_e32 v85, 0x21800000, v85
	v_max_f32_e32 v86, 0x21800000, v86
	v_max_f32_e32 v87, 0x21800000, v87
	v_pk_mul_f32 v[64:65], v[64:65], v[84:85]
	v_pk_mul_f32 v[66:67], v[66:67], v[86:87]
	v_cvt_pk_bf16_f32 v64, v64, v65
	v_cvt_pk_bf16_f32 v65, v66, v67
	v_lshlrev_b32_e32 v66, 16, v100
	v_and_b32_e32 v67, 0xffff0000, v100
	v_lshlrev_b32_e32 v84, 16, v101
	v_and_b32_e32 v85, 0xffff0000, v101
	v_max_f32_e32 v66, v66, v66
	v_max_f32_e32 v67, v67, v67
	v_max_f32_e32 v84, v84, v84
	v_max_f32_e32 v85, v85, v85
	v_max_f32_e32 v66, 0x21800000, v66
	v_max_f32_e32 v67, 0x21800000, v67
	v_max_f32_e32 v84, 0x21800000, v84
	v_max_f32_e32 v85, 0x21800000, v85
	v_pk_mul_f32 v[66:67], v[68:69], v[66:67]
	v_pk_mul_f32 v[68:69], v[70:71], v[84:85]
	v_cvt_pk_bf16_f32 v66, v66, v67
	v_cvt_pk_bf16_f32 v67, v68, v69
	ds_write2_b64 v212, v[64:65], v[66:67] offset0:24 offset1:26
	s_waitcnt vmcnt(0)
	v_lshlrev_b32_e32 v64, 16, v80
	v_and_b32_e32 v65, 0xffff0000, v80
	v_lshlrev_b32_e32 v66, 16, v81
	v_and_b32_e32 v67, 0xffff0000, v81
	v_max_f32_e32 v64, v64, v64
	v_max_f32_e32 v65, v65, v65
	v_max_f32_e32 v66, v66, v66
	v_max_f32_e32 v67, v67, v67
	v_max_f32_e32 v64, 0x21800000, v64
	v_max_f32_e32 v65, 0x21800000, v65
	v_max_f32_e32 v66, 0x21800000, v66
	v_max_f32_e32 v67, 0x21800000, v67
	v_pk_mul_f32 v[64:65], v[72:73], v[64:65]
	v_pk_mul_f32 v[66:67], v[74:75], v[66:67]
	v_cvt_pk_bf16_f32 v64, v64, v65
	v_cvt_pk_bf16_f32 v65, v66, v67
	v_lshlrev_b32_e32 v66, 16, v82
	v_and_b32_e32 v67, 0xffff0000, v82
	v_lshlrev_b32_e32 v68, 16, v83
	v_and_b32_e32 v69, 0xffff0000, v83
	v_max_f32_e32 v66, v66, v66
	v_max_f32_e32 v67, v67, v67
	v_max_f32_e32 v68, v68, v68
	v_max_f32_e32 v69, v69, v69
	v_max_f32_e32 v66, 0x21800000, v66
	v_max_f32_e32 v67, 0x21800000, v67
	v_max_f32_e32 v68, 0x21800000, v68
	v_max_f32_e32 v69, 0x21800000, v69
	v_pk_mul_f32 v[66:67], v[76:77], v[66:67]
	v_pk_mul_f32 v[68:69], v[78:79], v[68:69]
	v_cvt_pk_bf16_f32 v66, v66, v67
	v_cvt_pk_bf16_f32 v67, v68, v69
	ds_write2_b64 v212, v[64:65], v[66:67] offset0:28 offset1:30
	s_waitcnt lgkmcnt(0)
	s_barrier
; DI u32x2 pk4(float a, float b, float c, float d) { u32x2 r; r.x = pk2(a, b); r.y = pk2(c, d); return r; }
; DI float bf_lo(unsigned u) { return __uint_as_float(u << 16); }
; DI float bf_hi(unsigned u) { return __uint_as_float(u & 0xffff0000u); }
; template <int WI, int WGJ, class GetF, class FinF>
; DI void staged_rows(unsigned char* lds, int tid, GetF get, FinF fin) {
;     ...
; #pragma unroll 1
;         for (int c = 0; c < ROWS * NCH / NT; ++c) {
;             const int idx = tid + c * NT, lr = idx / NCH, ch = idx % NCH;
;             const u32x4 v = *(const u32x4*)(lds + lr * RS + ch * 16);
;             fin((lr >> 5) * 64 + jt * 32 + (lr & 31), ch * 8, v);
;         }
; DI void phase4(const Params& p, unsigned char* smem, int tid) {
;     ...
;             staged_rows<4, 4>(lds, te,
;                 [&](int it, int jt, int g) { const u32x4 b4 = *(const u32x4*)(gb + ((it * 2 + jt) * 2 + (g >> 1)) * 1024); const int e0 = (g & 1) * 2;
;                     const float g0 = fmaxf(bf_lo(b4[e0]), 8.6736174e-19f), g1 = fmaxf(bf_hi(b4[e0]), 8.6736174e-19f);
;                     const float g2 = fmaxf(bf_lo(b4[e0 + 1]), 8.6736174e-19f), g3 = fmaxf(bf_hi(b4[e0 + 1]), 8.6736174e-19f);
;                     return pk4(acc[it][jt][4 * g] * g0, acc[it][jt][4 * g + 1] * g1, acc[it][jt][4 * g + 2] * g2, acc[it][jt][4 * g + 3] * g3); },
;                 [&](int row, int col, u32x4 v) { __builtin_nontemporal_store(v, (u32x4*)(mx + (size_t)(r0 + row) * 1024 + f * 256 + col)); });
.LBB0_997:
	s_nop 0
	v_add_u32_e32 v64, s6, v221
	v_ashrrev_i32_e32 v65, 31, v64
	v_lshrrev_b32_e32 v65, 27, v65
	v_add_u32_e32 v65, v64, v65
	v_ashrrev_i32_e32 v66, 5, v65
	v_and_b32_e32 v65, 0xffffffe0, v65
	v_sub_u32_e32 v64, v64, v65
	v_mul_lo_u32 v65, v66, s50
	v_lshlrev_b32_e32 v67, 1, v66
	v_lshlrev_b32_e32 v69, 4, v64
	v_and_b32_e32 v66, 31, v66
	v_and_b32_e32 v67, 0xffffffc0, v67
	v_lshlrev_b32_e32 v68, 3, v64
	v_add3_u32 v64, 0, v65, v69
	v_add3_u32 v70, v66, s10, v67
	ds_read_b128 v[64:67], v64 offset:2048
	v_ashrrev_i32_e32 v71, 31, v70
	v_lshlrev_b64 v[70:71], 11, v[70:71]
	s_addk_i32 s6, 0x200
	v_ashrrev_i32_e32 v69, 31, v68
	v_lshl_add_u64 v[70:71], s[12:13], 0, v[70:71]
	s_cmpk_eq_i32 s6, 0x1000
	v_lshl_add_u64 v[68:69], v[68:69], 1, v[70:71]
	s_waitcnt lgkmcnt(0)
	global_store_dwordx4 v[68:69], v[64:67], off nt
	s_cbranch_scc0 .LBB0_997
	s_barrier
	global_load_dwordx4 v[76:79], v[216:217], off offset:2048 nt
	global_load_dwordx4 v[80:83], v[216:217], off offset:3072 nt
	global_load_dwordx4 v[72:75], v[218:219], off offset:2048 nt
	global_load_dwordx4 v[68:71], v[218:219], off offset:3072 nt
	global_load_dwordx4 v[64:67], v[214:215], off offset:2048 nt
	v_mfma_f32_32x32x16_bf16 v[0:15], v[144:147], v[128:131], v[0:15]
	s_mov_b32 s6, 0
	s_add_i32 s10, s10, 32
	s_waitcnt vmcnt(4)
	v_lshlrev_b32_e32 v84, 16, v76
	v_mfma_f32_32x32x16_bf16 v[32:47], v[140:143], v[128:131], v[32:47]
	v_and_b32_e32 v76, 0xffff0000, v76
	v_lshlrev_b32_e32 v85, 16, v77
	v_and_b32_e32 v77, 0xffff0000, v77
	v_lshlrev_b32_e32 v86, 16, v78
	v_and_b32_e32 v78, 0xffff0000, v78
	v_lshlrev_b32_e32 v87, 16, v79
	v_and_b32_e32 v79, 0xffff0000, v79
	v_mfma_f32_32x32x16_bf16 v[0:15], v[200:203], v[188:191], v[0:15]
	s_waitcnt vmcnt(3)
	v_lshlrev_b32_e32 v88, 16, v80
	v_and_b32_e32 v80, 0xffff0000, v80
	v_lshlrev_b32_e32 v89, 16, v81
	v_and_b32_e32 v81, 0xffff0000, v81
	v_lshlrev_b32_e32 v90, 16, v82
	v_and_b32_e32 v82, 0xffff0000, v82
	v_lshlrev_b32_e32 v91, 16, v83
	v_mfma_f32_32x32x16_bf16 v[32:47], v[204:207], v[188:191], v[32:47]
	v_and_b32_e32 v83, 0xffff0000, v83
	v_max_f32_e32 v84, v84, v84
	v_max_f32_e32 v93, v76, v76
	v_max_f32_e32 v85, v85, v85
	v_max_f32_e32 v94, v77, v77
	v_max_f32_e32 v86, v86, v86
	v_max_f32_e32 v95, v78, v78
	v_mfma_f32_32x32x16_bf16 v[0:15], v[184:187], v[164:167], v[0:15]
	v_max_f32_e32 v87, v87, v87
	v_max_f32_e32 v98, v79, v79
	v_max_f32_e32 v88, v88, v88
	v_max_f32_e32 v99, v80, v80
	v_max_f32_e32 v89, v89, v89
	v_max_f32_e32 v100, v81, v81
	v_max_f32_e32 v90, v90, v90
	v_mfma_f32_32x32x16_bf16 v[32:47], v[176:179], v[164:167], v[32:47]
	v_max_f32_e32 v101, v82, v82
	v_max_f32_e32 v91, v91, v91
	v_max_f32_e32 v102, v83, v83
	v_max_f32_e32 v76, 0x21800000, v84
	v_max_f32_e32 v77, 0x21800000, v93
	v_max_f32_e32 v78, 0x21800000, v85
	v_max_f32_e32 v79, 0x21800000, v94
	v_mfma_f32_32x32x16_bf16 v[0:15], v[180:183], v[160:163], v[0:15]
	v_max_f32_e32 v80, 0x21800000, v86
	v_max_f32_e32 v81, 0x21800000, v95
	v_max_f32_e32 v82, 0x21800000, v87
	v_max_f32_e32 v83, 0x21800000, v98
	v_max_f32_e32 v84, 0x21800000, v88
	v_max_f32_e32 v85, 0x21800000, v99
	v_max_f32_e32 v86, 0x21800000, v89
	v_mfma_f32_32x32x16_bf16 v[48:63], v[136:139], v[128:131], v[48:63]
	v_max_f32_e32 v87, 0x21800000, v100
	v_max_f32_e32 v88, 0x21800000, v90
	v_max_f32_e32 v89, 0x21800000, v101
	v_max_f32_e32 v90, 0x21800000, v91
	v_max_f32_e32 v91, 0x21800000, v102
	v_pk_mul_f32 v[0:1], v[0:1], v[76:77]
	v_pk_mul_f32 v[2:3], v[2:3], v[78:79]
	v_mfma_f32_32x32x16_bf16 v[32:47], v[156:159], v[160:163], v[32:47]
	v_mul_f32_e64 v4, v4, v80
	v_mul_f32_e64 v5, v5, v81
	v_mul_f32_e64 v6, v6, v82
	v_mul_f32_e64 v7, v7, v83
	v_mul_f32_e64 v8, v8, v84
	v_mul_f32_e64 v9, v9, v85
	v_pk_mul_f32 v[10:11], v[10:11], v[86:87]
	v_pk_mul_f32 v[12:13], v[12:13], v[88:89]
	v_pk_mul_f32 v[14:15], v[14:15], v[90:91]
	v_cvt_pk_bf16_f32 v0, v0, v1
	v_cvt_pk_bf16_f32 v1, v2, v3
	v_cvt_pk_bf16_f32 v2, v4, v5
	v_cvt_pk_bf16_f32 v3, v6, v7
	s_waitcnt vmcnt(2)
	v_lshlrev_b32_e32 v92, 16, v72
	v_cvt_pk_bf16_f32 v4, v8, v9
	v_cvt_pk_bf16_f32 v5, v10, v11
	v_cvt_pk_bf16_f32 v6, v12, v13
	v_cvt_pk_bf16_f32 v7, v14, v15
	ds_write2_b64 v212, v[0:1], v[2:3] offset1:2
	ds_write2_b64 v212, v[4:5], v[6:7] offset0:4 offset1:6
	v_and_b32_e32 v1, 0xffff0000, v72
	v_max_f32_e32 v0, v92, v92
	v_max_f32_e32 v1, v1, v1
	v_max_f32_e32 v0, 0x21800000, v0
	v_max_f32_e32 v1, 0x21800000, v1
	v_mfma_f32_32x32x16_bf16 v[48:63], v[192:195], v[188:191], v[48:63]
	v_mul_f32_e64 v0, v32, v0
	v_mul_f32_e64 v1, v33, v1
	v_lshlrev_b32_e32 v2, 16, v73
	v_cvt_pk_bf16_f32 v4, v0, v1
	v_lshlrev_b32_e32 v0, 16, v74
	v_max_f32_e32 v0, v0, v0
	v_and_b32_e32 v3, 0xffff0000, v73
	v_max_f32_e32 v6, 0x21800000, v0
	v_and_b32_e32 v0, 0xffff0000, v74
	v_max_f32_e32 v2, v2, v2
	v_max_f32_e32 v3, v3, v3
	v_max_f32_e32 v0, v0, v0
	v_max_f32_e32 v2, 0x21800000, v2
	v_max_f32_e32 v3, 0x21800000, v3
	v_max_f32_e32 v7, 0x21800000, v0
	v_lshlrev_b32_e32 v0, 16, v75
	v_and_b32_e32 v9, 0xffff0000, v75
	v_pk_mul_f32 v[2:3], v[34:35], v[2:3]
	v_max_f32_e32 v8, v0, v0
	v_max_f32_e32 v9, v9, v9
	v_cvt_pk_bf16_f32 v5, v2, v3
	global_load_dwordx4 v[0:3], v[214:215], off offset:3072 nt
	v_max_f32_e32 v8, 0x21800000, v8
	v_max_f32_e32 v9, 0x21800000, v9
	v_mfma_f32_32x32x16_bf16 v[48:63], v[172:175], v[164:167], v[48:63]
	v_mul_f32_e64 v6, v36, v6
	v_mul_f32_e64 v7, v37, v7
	v_mul_f32_e64 v8, v38, v8
	v_mul_f32_e64 v9, v39, v9
	v_cvt_pk_bf16_f32 v6, v6, v7
	v_cvt_pk_bf16_f32 v7, v8, v9
	ds_write2_b64 v212, v[4:5], v[6:7] offset0:8 offset1:10
	s_waitcnt vmcnt(2)
; DI u32x2 pk4(float a, float b, float c, float d) { u32x2 r; r.x = pk2(a, b); r.y = pk2(c, d); return r; }
; DI float bf_lo(unsigned u) { return __uint_as_float(u << 16); }
; DI float bf_hi(unsigned u) { return __uint_as_float(u & 0xffff0000u); }
; template <int WI, int WGJ, class GetF, class FinF>
; DI void staged_rows(unsigned char* lds, int tid, GetF get, FinF fin) {
;     ...
;     for (int jt = 0; jt < 2; ++jt) {
;         unsigned char* wrow = lds + (wj * 32 + ln) * RS + (wi * WI * 32 + 4 * h) * 2;
; #pragma unroll
;         for (int it = 0; it < WI; ++it)
; #pragma unroll
;             for (int g = 0; g < 4; ++g) *(u32x2*)(wrow + (it * 32 + 8 * g) * 2) = get(it, jt, g);
;         __syncthreads();
; DI void phase4(const Params& p, unsigned char* smem, int tid) {
;     ...
;                 [&](int it, int jt, int g) { const u32x4 b4 = *(const u32x4*)(gb + ((it * 2 + jt) * 2 + (g >> 1)) * 1024); const int e0 = (g & 1) * 2;
;                     const float g0 = fmaxf(bf_lo(b4[e0]), 8.6736174e-19f), g1 = fmaxf(bf_hi(b4[e0]), 8.6736174e-19f);
;                     const float g2 = fmaxf(bf_lo(b4[e0 + 1]), 8.6736174e-19f), g3 = fmaxf(bf_hi(b4[e0 + 1]), 8.6736174e-19f);
;                     return pk4(acc[it][jt][4 * g] * g0, acc[it][jt][4 * g + 1] * g1, acc[it][jt][4 * g + 2] * g2, acc[it][jt][4 * g + 3] * g3); },
	v_lshlrev_b32_e32 v4, 16, v68
	v_and_b32_e32 v5, 0xffff0000, v68
	v_max_f32_e32 v4, v4, v4
	v_max_f32_e32 v5, v5, v5
	v_max_f32_e32 v4, 0x21800000, v4
	v_max_f32_e32 v5, 0x21800000, v5
	v_pk_mul_f32 v[4:5], v[40:41], v[4:5]
	v_lshlrev_b32_e32 v6, 16, v69
	v_and_b32_e32 v7, 0xffff0000, v69
	v_cvt_pk_bf16_f32 v8, v4, v5
	v_lshlrev_b32_e32 v4, 16, v70
	v_max_f32_e32 v6, v6, v6
	v_max_f32_e32 v7, v7, v7
	v_max_f32_e32 v4, v4, v4
	v_mfma_f32_32x32x16_bf16 v[48:63], v[152:155], v[160:163], v[48:63]
	v_max_f32_e32 v6, 0x21800000, v6
	v_max_f32_e32 v7, 0x21800000, v7
	v_max_f32_e32 v10, 0x21800000, v4
	v_and_b32_e32 v4, 0xffff0000, v70
	v_lshlrev_b32_e32 v12, 16, v71
	v_and_b32_e32 v13, 0xffff0000, v71
	v_pk_mul_f32 v[6:7], v[42:43], v[6:7]
	v_max_f32_e32 v11, v4, v4
	v_max_f32_e32 v12, v12, v12
	v_max_f32_e32 v13, v13, v13
	v_cvt_pk_bf16_f32 v9, v6, v7
	global_load_dwordx4 v[4:7], v[96:97], off offset:2048 nt
	v_max_f32_e32 v11, 0x21800000, v11
	v_max_f32_e32 v12, 0x21800000, v12
	v_max_f32_e32 v13, 0x21800000, v13
	v_pk_mul_f32 v[10:11], v[44:45], v[10:11]
	v_pk_mul_f32 v[12:13], v[46:47], v[12:13]
	v_cvt_pk_bf16_f32 v10, v10, v11
	v_cvt_pk_bf16_f32 v11, v12, v13
	ds_write2_b64 v212, v[8:9], v[10:11] offset0:12 offset1:14
	s_waitcnt vmcnt(2)
	v_lshlrev_b32_e32 v8, 16, v64
	v_and_b32_e32 v9, 0xffff0000, v64
	v_max_f32_e32 v8, v8, v8
	v_max_f32_e32 v9, v9, v9
	v_max_f32_e32 v8, 0x21800000, v8
	v_max_f32_e32 v9, 0x21800000, v9
	v_lshlrev_b32_e32 v10, 16, v65
	v_and_b32_e32 v11, 0xffff0000, v65
	v_max_f32_e32 v10, v10, v10
	v_max_f32_e32 v11, v11, v11
	v_pk_mul_f32 v[8:9], v[48:49], v[8:9]
	v_max_f32_e32 v10, 0x21800000, v10
	v_max_f32_e32 v11, 0x21800000, v11
	v_cvt_pk_bf16_f32 v12, v8, v9
	v_lshlrev_b32_e32 v8, 16, v66
	v_pk_mul_f32 v[10:11], v[50:51], v[10:11]
	v_max_f32_e32 v8, v8, v8
	v_cvt_pk_bf16_f32 v13, v10, v11
	v_max_f32_e32 v14, 0x21800000, v8
	global_load_dwordx4 v[8:11], v[96:97], off offset:3072 nt
	v_mfma_f32_32x32x16_bf16 v[16:31], v[132:135], v[128:131], v[16:31]
	v_and_b32_e32 v15, 0xffff0000, v66
	v_lshlrev_b32_e32 v32, 16, v67
	v_and_b32_e32 v33, 0xffff0000, v67
	v_max_f32_e32 v15, v15, v15
	v_max_f32_e32 v32, v32, v32
	v_max_f32_e32 v33, v33, v33
	v_max_f32_e32 v15, 0x21800000, v15
	v_mfma_f32_32x32x16_bf16 v[16:31], v[196:199], v[188:191], v[16:31]
	v_max_f32_e32 v32, 0x21800000, v32
	v_max_f32_e32 v33, 0x21800000, v33
	v_mul_f32_e64 v14, v52, v14
	v_mul_f32_e64 v15, v53, v15
	v_mul_f32_e64 v32, v54, v32
	v_mul_f32_e64 v33, v55, v33
	v_cvt_pk_bf16_f32 v14, v14, v15
	v_cvt_pk_bf16_f32 v15, v32, v33
	ds_write2_b64 v212, v[12:13], v[14:15] offset0:16 offset1:18
	v_mfma_f32_32x32x16_bf16 v[16:31], v[168:171], v[164:167], v[16:31]
	s_waitcnt vmcnt(2)
	v_lshlrev_b32_e32 v12, 16, v0
	v_and_b32_e32 v0, 0xffff0000, v0
	v_max_f32_e32 v0, v0, v0
	v_max_f32_e32 v13, 0x21800000, v0
	v_lshlrev_b32_e32 v0, 16, v1
	v_and_b32_e32 v1, 0xffff0000, v1
	v_max_f32_e32 v12, v12, v12
	v_max_f32_e32 v0, v0, v0
	v_max_f32_e32 v1, v1, v1
	v_max_f32_e32 v12, 0x21800000, v12
	v_max_f32_e32 v0, 0x21800000, v0
	v_max_f32_e32 v1, 0x21800000, v1
	v_pk_mul_f32 v[12:13], v[56:57], v[12:13]
	v_pk_mul_f32 v[0:1], v[58:59], v[0:1]
	v_mfma_f32_32x32x16_bf16 v[16:31], v[148:151], v[160:163], v[16:31]
	v_cvt_pk_bf16_f32 v12, v12, v13
	v_cvt_pk_bf16_f32 v13, v0, v1
	v_lshlrev_b32_e32 v0, 16, v2
	v_and_b32_e32 v1, 0xffff0000, v2
	v_lshlrev_b32_e32 v2, 16, v3
	v_and_b32_e32 v3, 0xffff0000, v3
	v_max_f32_e32 v0, v0, v0
	v_max_f32_e32 v1, v1, v1
	v_max_f32_e32 v2, v2, v2
	v_max_f32_e32 v3, v3, v3
	v_max_f32_e32 v0, 0x21800000, v0
	v_max_f32_e32 v1, 0x21800000, v1
	v_max_f32_e32 v2, 0x21800000, v2
	v_max_f32_e32 v3, 0x21800000, v3
	v_pk_mul_f32 v[0:1], v[60:61], v[0:1]
	v_pk_mul_f32 v[2:3], v[62:63], v[2:3]
	v_cvt_pk_bf16_f32 v0, v0, v1
	v_cvt_pk_bf16_f32 v1, v2, v3
	ds_write2_b64 v212, v[12:13], v[0:1] offset0:20 offset1:22
	s_waitcnt vmcnt(1)
	v_lshlrev_b32_e32 v0, 16, v4
	v_and_b32_e32 v1, 0xffff0000, v4
	v_lshlrev_b32_e32 v2, 16, v5
	v_and_b32_e32 v3, 0xffff0000, v5
	v_max_f32_e32 v0, v0, v0
	v_max_f32_e32 v1, v1, v1
	v_max_f32_e32 v2, v2, v2
	v_max_f32_e32 v3, v3, v3
	v_max_f32_e32 v0, 0x21800000, v0
	v_max_f32_e32 v1, 0x21800000, v1
	v_max_f32_e32 v2, 0x21800000, v2
	v_max_f32_e32 v3, 0x21800000, v3
	v_pk_mul_f32 v[0:1], v[16:17], v[0:1]
	v_pk_mul_f32 v[2:3], v[18:19], v[2:3]
	v_cvt_pk_bf16_f32 v0, v0, v1
	v_cvt_pk_bf16_f32 v1, v2, v3
	v_lshlrev_b32_e32 v2, 16, v6
	v_and_b32_e32 v3, 0xffff0000, v6
	v_lshlrev_b32_e32 v4, 16, v7
	v_and_b32_e32 v5, 0xffff0000, v7
	v_max_f32_e32 v2, v2, v2
	v_max_f32_e32 v3, v3, v3
	v_max_f32_e32 v4, v4, v4
	v_max_f32_e32 v5, v5, v5
	v_max_f32_e32 v2, 0x21800000, v2
	v_max_f32_e32 v3, 0x21800000, v3
	v_max_f32_e32 v4, 0x21800000, v4
	v_max_f32_e32 v5, 0x21800000, v5
	v_pk_mul_f32 v[2:3], v[20:21], v[2:3]
	v_pk_mul_f32 v[4:5], v[22:23], v[4:5]
	v_cvt_pk_bf16_f32 v2, v2, v3
	v_cvt_pk_bf16_f32 v3, v4, v5
	ds_write2_b64 v212, v[0:1], v[2:3] offset0:24 offset1:26
	s_waitcnt vmcnt(0)
	v_lshlrev_b32_e32 v0, 16, v8
	v_and_b32_e32 v1, 0xffff0000, v8
	v_lshlrev_b32_e32 v2, 16, v9
	v_and_b32_e32 v3, 0xffff0000, v9
	v_max_f32_e32 v0, v0, v0
	v_max_f32_e32 v1, v1, v1
	v_max_f32_e32 v2, v2, v2
	v_max_f32_e32 v3, v3, v3
	v_max_f32_e32 v0, 0x21800000, v0
	v_max_f32_e32 v1, 0x21800000, v1
	v_max_f32_e32 v2, 0x21800000, v2
	v_max_f32_e32 v3, 0x21800000, v3
	v_pk_mul_f32 v[0:1], v[24:25], v[0:1]
	v_pk_mul_f32 v[2:3], v[26:27], v[2:3]
	v_cvt_pk_bf16_f32 v0, v0, v1
	v_cvt_pk_bf16_f32 v1, v2, v3
	v_lshlrev_b32_e32 v2, 16, v10
	v_and_b32_e32 v3, 0xffff0000, v10
	v_lshlrev_b32_e32 v4, 16, v11
	v_and_b32_e32 v5, 0xffff0000, v11
	v_max_f32_e32 v2, v2, v2
	v_max_f32_e32 v3, v3, v3
	v_max_f32_e32 v4, v4, v4
	v_max_f32_e32 v5, v5, v5
	v_max_f32_e32 v2, 0x21800000, v2
	v_max_f32_e32 v3, 0x21800000, v3
	v_max_f32_e32 v4, 0x21800000, v4
	v_max_f32_e32 v5, 0x21800000, v5
	v_pk_mul_f32 v[2:3], v[28:29], v[2:3]
	v_pk_mul_f32 v[4:5], v[30:31], v[4:5]
	v_cvt_pk_bf16_f32 v2, v2, v3
	v_cvt_pk_bf16_f32 v3, v4, v5
	ds_write2_b64 v212, v[0:1], v[2:3] offset0:28 offset1:30
	s_waitcnt lgkmcnt(0)
	s_barrier
